# first wait of each tile's (peeled) first K-iteration relaxed to a counted vmcnt that leaves the previous epilogue's stores/atomics and the next row-stat prefetch in flight (the DMAs it guards are alre
# baseline (speedup 1.0000x reference)
; #define PG8_STAGE(bufoff, gbase, voff) do { _Pragma("unroll") for (int _i = 0; _i < 2; ++_i) \
;         __builtin_amdgcn_global_load_lds((const unsigned*)((const char*)(gbase) + (voff)[_i]), (PG8_LAS unsigned*)(lds + (bufoff) + ldsw + _i * 8192), 16, 0, 0); } while (0)
; #define PG8_LDA(dst, b, h) do { _Pragma("unroll") for (int m = 0; m < 4; ++m) _Pragma("unroll") for (int k = 0; k < 2; ++k) dst[m][k] = *(const PG8_LAS bf16x8*)(lds + PG8_SA(b, h) + aoff + m * 2048 + k * 1024); } while (0)
; #define PG8_LDB(dst, b, h) do { _Pragma("unroll") for (int n = 0; n < 2; ++n) _Pragma("unroll") for (int k = 0; k < 2; ++k) dst[n][k] = *(const PG8_LAS bf16x8*)(lds + PG8_SB(b, h) + boff + n * 2048 + k * 1024); } while (0)
; #define PG8_MMA(ai, bj, At, Bt) do { __builtin_amdgcn_s_setprio(1); _Pragma("unroll") for (int m = 0; m < 4; ++m) _Pragma("unroll") for (int n = 0; n < 2; ++n) _Pragma("unroll") for (int k = 0; k < 2; ++k) \
;         acc[ai][bj][m][n] = __builtin_amdgcn_mfma_f32_16x16x32_bf16(Bt[n][k], At[m][k], acc[ai][bj][m][n], 0, 0, 0); __builtin_amdgcn_s_setprio(0); } while (0)
; #define PG8_WAIT_V(n) asm volatile("s_waitcnt vmcnt(" #n ")" ::: "memory")
; #define PG8_WAIT_L(n) asm volatile("s_waitcnt lgkmcnt(" #n ")" ::: "memory")
; #define PG8_BAR __builtin_amdgcn_s_barrier()
; #define PG8_SCHED __builtin_amdgcn_sched_barrier(0)
; template <class Epi, class Sched, bool ALIGN_EPI = false, bool SP2 = false>
; __device__ __forceinline__ void gemm_phase(PG8_LAS unsigned char* lds, const Gemm g, const Sched& S, const Epi& E) {
;     ...
;             PG8_LDB(B0, 0, 0); PG8_LDB(B1, 0, 1); PG8_SCHED; PG8_LDA(At, 0, 0); PG8_STAGE(PG8_SA(1, 1), a1 + hstep, voffA);
;             PG8_WAIT_V(8); PG8_WAIT_L(0); PG8_BAR; PG8_MMA(0, 0, At, B0); PG8_MMA(0, 1, At, B1); PG8_BAR; PG8_SCHED;
;             PG8_LDA(At, 0, 1); PG8_STAGE(PG8_SB(0, 0), b2, voffB); PG8_STAGE(PG8_SB(0, 1), b2 + hstep, voffB); PG8_STAGE(PG8_SA(0, 0), a2, voffA);
;             PG8_WAIT_V(8); PG8_WAIT_L(0); PG8_BAR; PG8_MMA(1, 0, At, B0); PG8_MMA(1, 1, At, B1); PG8_BAR; PG8_SCHED;
.LBB0_84:
	s_ashr_i32 s11, s10, 31
	s_lshl_b64 s[12:13], s[10:11], 20
	s_add_u32 s12, s46, s12
	s_addc_u32 s13, s47, s13
	s_and_b64 s[14:15], s[2:3], exec
	s_cselect_b32 s11, s13, s19
	s_cselect_b32 s42, s12, s18
	s_ashr_i32 s9, s8, 31
	s_lshl_b64 s[14:15], s[8:9], 20
	v_readlane_b32 s9, v255, 30
	s_add_u32 s14, s9, s14
	v_readlane_b32 s9, v255, 31
	s_addc_u32 s15, s9, s15
	s_and_b64 s[22:23], s[2:3], exec
	s_cselect_b32 s9, s15, s21
	s_cselect_b32 s44, s14, s20
	s_add_u32 s18, s18, 0x80080
	s_addc_u32 s19, s19, 0
	s_add_u32 s45, s20, 0x100
	s_addc_u32 s50, s21, 0
	s_mov_b32 s51, -2
	s_add_u32 s20, s18, 0xfff80080
	s_addc_u32 s21, s19, -1
	s_add_i32 s56, 0, 0x10000
	s_cmp_eq_u32 s51, 28
	s_cselect_b32 s23, s11, s21
	s_cselect_b32 s22, s42, s20
	v_add_u32_e32 v150, s56, v153
	s_cselect_b32 s21, s9, s50
	s_cselect_b32 s20, s44, s45
	s_add_i32 s63, 0, 0x14000
	ds_read_b128 v[184:187], v150
	ds_read_b128 v[188:191], v150 offset:1024
	ds_read_b128 v[192:195], v150 offset:2048
	ds_read_b128 v[196:199], v150 offset:3072
	v_add_u32_e32 v150, s63, v153
	ds_read_b128 v[200:203], v150
	ds_read_b128 v[204:207], v150 offset:1024
	ds_read_b128 v[208:211], v150 offset:2048
	ds_read_b128 v[212:215], v150 offset:3072
	s_add_i32 m0, s27, 0xc000
	ds_read_b128 v[216:219], v155
	ds_read_b128 v[220:223], v155 offset:1024
	ds_read_b128 v[224:227], v155 offset:2048
	ds_read_b128 v[228:231], v155 offset:3072
	ds_read_b128 v[232:235], v155 offset:4096
	ds_read_b128 v[236:239], v155 offset:5120
	ds_read_b128 v[240:243], v155 offset:6144
	ds_read_b128 v[244:247], v155 offset:7168
	global_load_lds_dwordx4 v136, s[18:19]
	s_add_i32 m0, s27, 0xe000
	s_nop 0
	global_load_lds_dwordx4 v138, s[18:19]
	s_waitcnt vmcnt(24)
	s_waitcnt lgkmcnt(0)
	s_setprio 1
	s_barrier
	v_mfma_f32_16x16x32_bf16 v[128:131], v[184:187], v[216:219], 0
	v_mfma_f32_16x16x32_bf16 v[120:123], v[192:195], v[216:219], 0
	v_mfma_f32_16x16x32_bf16 v[112:115], v[184:187], v[224:227], 0
	v_mfma_f32_16x16x32_bf16 v[104:107], v[192:195], v[224:227], 0
	v_mfma_f32_16x16x32_bf16 v[96:99], v[184:187], v[232:235], 0
	v_mfma_f32_16x16x32_bf16 v[88:91], v[192:195], v[232:235], 0
	v_mfma_f32_16x16x32_bf16 v[80:83], v[184:187], v[240:243], 0
	v_mfma_f32_16x16x32_bf16 v[72:75], v[192:195], v[240:243], 0
	v_mfma_f32_16x16x32_bf16 v[128:131], v[188:191], v[220:223], v[128:131]
	v_mfma_f32_16x16x32_bf16 v[120:123], v[196:199], v[220:223], v[120:123]
	v_mfma_f32_16x16x32_bf16 v[112:115], v[188:191], v[228:231], v[112:115]
	v_mfma_f32_16x16x32_bf16 v[104:107], v[196:199], v[228:231], v[104:107]
	v_mfma_f32_16x16x32_bf16 v[96:99], v[188:191], v[236:239], v[96:99]
	v_mfma_f32_16x16x32_bf16 v[88:91], v[196:199], v[236:239], v[88:91]
	v_mfma_f32_16x16x32_bf16 v[80:83], v[188:191], v[244:247], v[80:83]
	v_mfma_f32_16x16x32_bf16 v[72:75], v[196:199], v[244:247], v[72:75]
	v_mfma_f32_16x16x32_bf16 v[124:127], v[200:203], v[216:219], 0
	v_mfma_f32_16x16x32_bf16 v[116:119], v[208:211], v[216:219], 0
	v_mfma_f32_16x16x32_bf16 v[108:111], v[200:203], v[224:227], 0
	v_mfma_f32_16x16x32_bf16 v[100:103], v[208:211], v[224:227], 0
	v_mfma_f32_16x16x32_bf16 v[92:95], v[200:203], v[232:235], 0
	v_mfma_f32_16x16x32_bf16 v[84:87], v[208:211], v[232:235], 0
	v_mfma_f32_16x16x32_bf16 v[76:79], v[200:203], v[240:243], 0
	v_mfma_f32_16x16x32_bf16 v[68:71], v[208:211], v[240:243], 0
	v_mfma_f32_16x16x32_bf16 v[124:127], v[204:207], v[220:223], v[124:127]
	v_mfma_f32_16x16x32_bf16 v[116:119], v[212:215], v[220:223], v[116:119]
	v_mfma_f32_16x16x32_bf16 v[108:111], v[204:207], v[228:231], v[108:111]
	v_mfma_f32_16x16x32_bf16 v[100:103], v[212:215], v[228:231], v[100:103]
	v_mfma_f32_16x16x32_bf16 v[92:95], v[204:207], v[236:239], v[92:95]
	v_mfma_f32_16x16x32_bf16 v[84:87], v[212:215], v[236:239], v[84:87]
	v_mfma_f32_16x16x32_bf16 v[76:79], v[204:207], v[244:247], v[76:79]
	v_mfma_f32_16x16x32_bf16 v[68:71], v[212:215], v[244:247], v[68:71]
	s_barrier
	s_setprio 0
	s_add_i32 s56, s56, s25
	s_mov_b32 m0, s56
	ds_read_b128 v[216:219], v155 offset:16384
	ds_read_b128 v[220:223], v155 offset:17408
	ds_read_b128 v[224:227], v155 offset:18432
	ds_read_b128 v[228:231], v155 offset:19456
	ds_read_b128 v[232:235], v155 offset:20480
	ds_read_b128 v[236:239], v155 offset:21504
	ds_read_b128 v[240:243], v155 offset:22528
	ds_read_b128 v[244:247], v155 offset:23552
	global_load_lds_dwordx4 v2, s[20:21]
	s_add_i32 m0, s56, 0x2000
	s_add_u32 s56, s20, 0x80000
	s_addc_u32 s57, s21, 0
	s_add_i32 s63, s63, s25
	global_load_lds_dwordx4 v0, s[20:21]
	s_mov_b32 m0, s63
	v_lshl_add_u64 v[252:253], s[22:23], 0, v[132:133]
	global_load_lds_dwordx4 v2, s[56:57]
	s_add_i32 m0, s63, 0x2000
	s_nop 0
	global_load_lds_dwordx4 v0, s[56:57]
	v_lshl_add_u64 v[250:251], s[22:23], 0, v[134:135]
	s_mov_b32 m0, s27
	s_nop 0
	global_load_lds_dwordx4 v[250:251], off
	s_mov_b32 m0, s28
	s_nop 0
	global_load_lds_dwordx4 v[252:253], off
	s_waitcnt vmcnt(8)
	s_waitcnt lgkmcnt(0)
	s_setprio 1
	s_barrier
; #define PG8_STAGE(bufoff, gbase, voff) do { _Pragma("unroll") for (int _i = 0; _i < 2; ++_i) \
;         __builtin_amdgcn_global_load_lds((const unsigned*)((const char*)(gbase) + (voff)[_i]), (PG8_LAS unsigned*)(lds + (bufoff) + ldsw + _i * 8192), 16, 0, 0); } while (0)
; #define PG8_LDA(dst, b, h) do { _Pragma("unroll") for (int m = 0; m < 4; ++m) _Pragma("unroll") for (int k = 0; k < 2; ++k) dst[m][k] = *(const PG8_LAS bf16x8*)(lds + PG8_SA(b, h) + aoff + m * 2048 + k * 1024); } while (0)
; #define PG8_LDB(dst, b, h) do { _Pragma("unroll") for (int n = 0; n < 2; ++n) _Pragma("unroll") for (int k = 0; k < 2; ++k) dst[n][k] = *(const PG8_LAS bf16x8*)(lds + PG8_SB(b, h) + boff + n * 2048 + k * 1024); } while (0)
; #define PG8_MMA(ai, bj, At, Bt) do { __builtin_amdgcn_s_setprio(1); _Pragma("unroll") for (int m = 0; m < 4; ++m) _Pragma("unroll") for (int n = 0; n < 2; ++n) _Pragma("unroll") for (int k = 0; k < 2; ++k) \
;         acc[ai][bj][m][n] = __builtin_amdgcn_mfma_f32_16x16x32_bf16(Bt[n][k], At[m][k], acc[ai][bj][m][n], 0, 0, 0); __builtin_amdgcn_s_setprio(0); } while (0)
; #define PG8_WAIT_V(n) asm volatile("s_waitcnt vmcnt(" #n ")" ::: "memory")
; #define PG8_WAIT_L(n) asm volatile("s_waitcnt lgkmcnt(" #n ")" ::: "memory")
; #define PG8_BAR __builtin_amdgcn_s_barrier()
; #define PG8_SCHED __builtin_amdgcn_sched_barrier(0)
; template <class Epi, class Sched, bool ALIGN_EPI = false, bool SP2 = false>
; __device__ __forceinline__ void gemm_phase(PG8_LAS unsigned char* lds, const Gemm g, const Sched& S, const Epi& E) {
;     ...
;             PG8_WAIT_V(8); PG8_WAIT_L(0); PG8_BAR; PG8_MMA(1, 0, At, B0); PG8_MMA(1, 1, At, B1); PG8_BAR; PG8_SCHED;
;             PG8_LDB(B0, 1, 0); PG8_LDB(B1, 1, 1); PG8_SCHED; PG8_LDA(At, 1, 0); PG8_STAGE(PG8_SA(0, 1), a2 + hstep, voffA);
;             PG8_WAIT_V(8); PG8_WAIT_L(0); PG8_BAR; PG8_MMA(0, 0, At, B0); PG8_MMA(0, 1, At, B1); PG8_BAR; PG8_SCHED;
	v_mfma_f32_16x16x32_bf16 v[64:67], v[184:187], v[216:219], 0
	v_mfma_f32_16x16x32_bf16 v[56:59], v[192:195], v[216:219], 0
	v_mfma_f32_16x16x32_bf16 v[48:51], v[184:187], v[224:227], 0
	v_mfma_f32_16x16x32_bf16 v[40:43], v[192:195], v[224:227], 0
	v_mfma_f32_16x16x32_bf16 v[32:35], v[184:187], v[232:235], 0
	v_mfma_f32_16x16x32_bf16 v[24:27], v[192:195], v[232:235], 0
	v_mfma_f32_16x16x32_bf16 v[16:19], v[184:187], v[240:243], 0
	v_mfma_f32_16x16x32_bf16 v[8:11], v[192:195], v[240:243], 0
	v_mfma_f32_16x16x32_bf16 v[64:67], v[188:191], v[220:223], v[64:67]
	v_mfma_f32_16x16x32_bf16 v[56:59], v[196:199], v[220:223], v[56:59]
	v_mfma_f32_16x16x32_bf16 v[48:51], v[188:191], v[228:231], v[48:51]
	v_mfma_f32_16x16x32_bf16 v[40:43], v[196:199], v[228:231], v[40:43]
	v_mfma_f32_16x16x32_bf16 v[32:35], v[188:191], v[236:239], v[32:35]
	v_mfma_f32_16x16x32_bf16 v[24:27], v[196:199], v[236:239], v[24:27]
	v_mfma_f32_16x16x32_bf16 v[16:19], v[188:191], v[244:247], v[16:19]
	v_mfma_f32_16x16x32_bf16 v[8:11], v[196:199], v[244:247], v[8:11]
	v_mfma_f32_16x16x32_bf16 v[60:63], v[200:203], v[216:219], 0
	v_mfma_f32_16x16x32_bf16 v[52:55], v[208:211], v[216:219], 0
	v_mfma_f32_16x16x32_bf16 v[44:47], v[200:203], v[224:227], 0
	v_mfma_f32_16x16x32_bf16 v[36:39], v[208:211], v[224:227], 0
	v_mfma_f32_16x16x32_bf16 v[28:31], v[200:203], v[232:235], 0
	v_mfma_f32_16x16x32_bf16 v[20:23], v[208:211], v[232:235], 0
	v_mfma_f32_16x16x32_bf16 v[12:15], v[200:203], v[240:243], 0
	v_mfma_f32_16x16x32_bf16 v[4:7], v[208:211], v[240:243], 0
	v_mfma_f32_16x16x32_bf16 v[60:63], v[204:207], v[220:223], v[60:63]
	v_mfma_f32_16x16x32_bf16 v[52:55], v[212:215], v[220:223], v[52:55]
	v_mfma_f32_16x16x32_bf16 v[44:47], v[204:207], v[228:231], v[44:47]
	v_mfma_f32_16x16x32_bf16 v[36:39], v[212:215], v[228:231], v[36:39]
	v_mfma_f32_16x16x32_bf16 v[28:31], v[204:207], v[236:239], v[28:31]
	v_mfma_f32_16x16x32_bf16 v[20:23], v[212:215], v[236:239], v[20:23]
	v_mfma_f32_16x16x32_bf16 v[12:15], v[204:207], v[244:247], v[12:15]
	v_mfma_f32_16x16x32_bf16 v[4:7], v[212:215], v[244:247], v[4:7]
	s_barrier
	s_setprio 0
	s_add_i32 s56, 0, 0x18000
	v_add_u32_e32 v161, s56, v153
	s_add_i32 s57, 0, 0x1c000
	ds_read_b128 v[184:187], v161
	ds_read_b128 v[188:191], v161 offset:1024
	ds_read_b128 v[192:195], v161 offset:2048
	ds_read_b128 v[196:199], v161 offset:3072
	v_add_u32_e32 v161, s57, v153
	ds_read_b128 v[200:203], v161
	ds_read_b128 v[204:207], v161 offset:1024
	ds_read_b128 v[208:211], v161 offset:2048
	ds_read_b128 v[212:215], v161 offset:3072
	s_add_u32 s22, s22, 0x80000
	s_addc_u32 s23, s23, 0
	s_mov_b32 m0, s29
	ds_read_b128 v[216:219], v155 offset:32768
	ds_read_b128 v[220:223], v155 offset:33792
	ds_read_b128 v[224:227], v155 offset:34816
	ds_read_b128 v[228:231], v155 offset:35840
	ds_read_b128 v[232:235], v155 offset:36864
	ds_read_b128 v[236:239], v155 offset:37888
	ds_read_b128 v[240:243], v155 offset:38912
	ds_read_b128 v[244:247], v155 offset:39936
	global_load_lds_dwordx4 v134, s[22:23]
	s_mov_b32 m0, s30
	s_nop 0
	global_load_lds_dwordx4 v132, s[22:23]
	s_waitcnt vmcnt(8)
	s_waitcnt lgkmcnt(0)
	s_setprio 1
	s_barrier
	v_mfma_f32_16x16x32_bf16 v[128:131], v[184:187], v[216:219], v[128:131]
	v_mfma_f32_16x16x32_bf16 v[120:123], v[192:195], v[216:219], v[120:123]
	v_mfma_f32_16x16x32_bf16 v[112:115], v[184:187], v[224:227], v[112:115]
	v_mfma_f32_16x16x32_bf16 v[104:107], v[192:195], v[224:227], v[104:107]
	v_mfma_f32_16x16x32_bf16 v[96:99], v[184:187], v[232:235], v[96:99]
	v_mfma_f32_16x16x32_bf16 v[88:91], v[192:195], v[232:235], v[88:91]
	v_mfma_f32_16x16x32_bf16 v[80:83], v[184:187], v[240:243], v[80:83]
	v_mfma_f32_16x16x32_bf16 v[72:75], v[192:195], v[240:243], v[72:75]
	v_mfma_f32_16x16x32_bf16 v[128:131], v[188:191], v[220:223], v[128:131]
	v_mfma_f32_16x16x32_bf16 v[120:123], v[196:199], v[220:223], v[120:123]
	v_mfma_f32_16x16x32_bf16 v[112:115], v[188:191], v[228:231], v[112:115]
	v_mfma_f32_16x16x32_bf16 v[104:107], v[196:199], v[228:231], v[104:107]
	v_mfma_f32_16x16x32_bf16 v[96:99], v[188:191], v[236:239], v[96:99]
	v_mfma_f32_16x16x32_bf16 v[88:91], v[196:199], v[236:239], v[88:91]
	v_mfma_f32_16x16x32_bf16 v[80:83], v[188:191], v[244:247], v[80:83]
	v_mfma_f32_16x16x32_bf16 v[72:75], v[196:199], v[244:247], v[72:75]
	v_mfma_f32_16x16x32_bf16 v[124:127], v[200:203], v[216:219], v[124:127]
	v_mfma_f32_16x16x32_bf16 v[116:119], v[208:211], v[216:219], v[116:119]
	v_mfma_f32_16x16x32_bf16 v[108:111], v[200:203], v[224:227], v[108:111]
	v_mfma_f32_16x16x32_bf16 v[100:103], v[208:211], v[224:227], v[100:103]
	v_mfma_f32_16x16x32_bf16 v[92:95], v[200:203], v[232:235], v[92:95]
	v_mfma_f32_16x16x32_bf16 v[84:87], v[208:211], v[232:235], v[84:87]
	v_mfma_f32_16x16x32_bf16 v[76:79], v[200:203], v[240:243], v[76:79]
	v_mfma_f32_16x16x32_bf16 v[68:71], v[208:211], v[240:243], v[68:71]
	v_mfma_f32_16x16x32_bf16 v[124:127], v[204:207], v[220:223], v[124:127]
	v_mfma_f32_16x16x32_bf16 v[116:119], v[212:215], v[220:223], v[116:119]
	v_mfma_f32_16x16x32_bf16 v[108:111], v[204:207], v[228:231], v[108:111]
	v_mfma_f32_16x16x32_bf16 v[100:103], v[212:215], v[228:231], v[100:103]
	v_mfma_f32_16x16x32_bf16 v[92:95], v[204:207], v[236:239], v[92:95]
	v_mfma_f32_16x16x32_bf16 v[84:87], v[212:215], v[236:239], v[84:87]
	v_mfma_f32_16x16x32_bf16 v[76:79], v[204:207], v[244:247], v[76:79]
	v_mfma_f32_16x16x32_bf16 v[68:71], v[212:215], v[244:247], v[68:71]
	s_barrier
; #define PG8_STAGE(bufoff, gbase, voff) do { _Pragma("unroll") for (int _i = 0; _i < 2; ++_i) \
;         __builtin_amdgcn_global_load_lds((const unsigned*)((const char*)(gbase) + (voff)[_i]), (PG8_LAS unsigned*)(lds + (bufoff) + ldsw + _i * 8192), 16, 0, 0); } while (0)
; #define PG8_LDA(dst, b, h) do { _Pragma("unroll") for (int m = 0; m < 4; ++m) _Pragma("unroll") for (int k = 0; k < 2; ++k) dst[m][k] = *(const PG8_LAS bf16x8*)(lds + PG8_SA(b, h) + aoff + m * 2048 + k * 1024); } while (0)
; #define PG8_MMA(ai, bj, At, Bt) do { __builtin_amdgcn_s_setprio(1); _Pragma("unroll") for (int m = 0; m < 4; ++m) _Pragma("unroll") for (int n = 0; n < 2; ++n) _Pragma("unroll") for (int k = 0; k < 2; ++k) \
;         acc[ai][bj][m][n] = __builtin_amdgcn_mfma_f32_16x16x32_bf16(Bt[n][k], At[m][k], acc[ai][bj][m][n], 0, 0, 0); __builtin_amdgcn_s_setprio(0); } while (0)
; #define PG8_WAIT_V(n) asm volatile("s_waitcnt vmcnt(" #n ")" ::: "memory")
; #define PG8_WAIT_L(n) asm volatile("s_waitcnt lgkmcnt(" #n ")" ::: "memory")
; #define PG8_BAR __builtin_amdgcn_s_barrier()
; #define PG8_SCHED __builtin_amdgcn_sched_barrier(0)
; template <class Epi, class Sched, bool ALIGN_EPI = false, bool SP2 = false>
; __device__ __forceinline__ void gemm_phase(PG8_LAS unsigned char* lds, const Gemm g, const Sched& S, const Epi& E) {
;     ...
;             PG8_LDA(At, 1, 1); PG8_STAGE(PG8_SB(1, 0), b3, voffB); PG8_STAGE(PG8_SB(1, 1), b3 + hstep, voffB); PG8_STAGE(PG8_SA(1, 0), a3, voffA);
;             PG8_WAIT_V(8); PG8_WAIT_L(0); PG8_BAR; PG8_MMA(1, 0, At, B0); PG8_MMA(1, 1, At, B1); PG8_BAR; PG8_SCHED;
	s_setprio 0
	s_add_i32 s22, s56, s25
	s_mov_b32 m0, s22
	ds_read_b128 v[216:219], v155 offset:49152
	ds_read_b128 v[220:223], v155 offset:50176
	ds_read_b128 v[224:227], v155 offset:51200
	ds_read_b128 v[228:231], v155 offset:52224
	ds_read_b128 v[232:235], v155 offset:53248
	ds_read_b128 v[236:239], v155 offset:54272
	ds_read_b128 v[240:243], v155 offset:55296
	ds_read_b128 v[244:247], v155 offset:56320
	s_add_u32 vcc_lo, s20, 0x80
	s_addc_u32 vcc_hi, s21, 0
	global_load_lds_dwordx4 v2, vcc
	s_add_i32 m0, s22, 0x2000
	s_add_u32 s20, s20, 0x80080
	s_addc_u32 s21, s21, 0
	s_add_i32 s22, s57, s25
	s_add_u32 vcc_lo, s20, 0xfff80000
	s_addc_u32 vcc_hi, s21, -1
	global_load_lds_dwordx4 v0, vcc
	s_mov_b32 m0, s22
	s_nop 0
	global_load_lds_dwordx4 v2, s[20:21]
	s_add_i32 m0, s22, 0x2000
	s_nop 0
	global_load_lds_dwordx4 v0, s[20:21]
	v_lshl_add_u64 v[150:151], v[250:251], 0, s[36:37]
	s_mov_b32 m0, s31
	s_nop 0
	global_load_lds_dwordx4 v[150:151], off
	v_lshl_add_u64 v[150:151], v[252:253], 0, s[36:37]
	s_mov_b32 m0, s34
	s_nop 0
	global_load_lds_dwordx4 v[150:151], off
	s_waitcnt vmcnt(8)
	s_waitcnt lgkmcnt(0)
	s_setprio 1
	s_barrier
	v_mfma_f32_16x16x32_bf16 v[64:67], v[184:187], v[216:219], v[64:67]
	v_mfma_f32_16x16x32_bf16 v[56:59], v[192:195], v[216:219], v[56:59]
	v_mfma_f32_16x16x32_bf16 v[48:51], v[184:187], v[224:227], v[48:51]
	v_mfma_f32_16x16x32_bf16 v[40:43], v[192:195], v[224:227], v[40:43]
	v_mfma_f32_16x16x32_bf16 v[32:35], v[184:187], v[232:235], v[32:35]
	v_mfma_f32_16x16x32_bf16 v[24:27], v[192:195], v[232:235], v[24:27]
	v_mfma_f32_16x16x32_bf16 v[16:19], v[184:187], v[240:243], v[16:19]
	v_mfma_f32_16x16x32_bf16 v[8:11], v[192:195], v[240:243], v[8:11]
	v_mfma_f32_16x16x32_bf16 v[64:67], v[188:191], v[220:223], v[64:67]
	v_mfma_f32_16x16x32_bf16 v[56:59], v[196:199], v[220:223], v[56:59]
	v_mfma_f32_16x16x32_bf16 v[48:51], v[188:191], v[228:231], v[48:51]
	v_mfma_f32_16x16x32_bf16 v[40:43], v[196:199], v[228:231], v[40:43]
	v_mfma_f32_16x16x32_bf16 v[32:35], v[188:191], v[236:239], v[32:35]
	v_mfma_f32_16x16x32_bf16 v[24:27], v[196:199], v[236:239], v[24:27]
	v_mfma_f32_16x16x32_bf16 v[16:19], v[188:191], v[244:247], v[16:19]
	v_mfma_f32_16x16x32_bf16 v[8:11], v[196:199], v[244:247], v[8:11]
	v_mfma_f32_16x16x32_bf16 v[60:63], v[200:203], v[216:219], v[60:63]
	v_mfma_f32_16x16x32_bf16 v[52:55], v[208:211], v[216:219], v[52:55]
	v_mfma_f32_16x16x32_bf16 v[44:47], v[200:203], v[224:227], v[44:47]
	v_mfma_f32_16x16x32_bf16 v[36:39], v[208:211], v[224:227], v[36:39]
	v_mfma_f32_16x16x32_bf16 v[28:31], v[200:203], v[232:235], v[28:31]
	v_mfma_f32_16x16x32_bf16 v[20:23], v[208:211], v[232:235], v[20:23]
	v_mfma_f32_16x16x32_bf16 v[12:15], v[200:203], v[240:243], v[12:15]
	v_mfma_f32_16x16x32_bf16 v[4:7], v[208:211], v[240:243], v[4:7]
	v_mfma_f32_16x16x32_bf16 v[60:63], v[204:207], v[220:223], v[60:63]
	v_mfma_f32_16x16x32_bf16 v[52:55], v[212:215], v[220:223], v[52:55]
	v_mfma_f32_16x16x32_bf16 v[44:47], v[204:207], v[228:231], v[44:47]
	v_mfma_f32_16x16x32_bf16 v[36:39], v[212:215], v[228:231], v[36:39]
	v_mfma_f32_16x16x32_bf16 v[28:31], v[204:207], v[236:239], v[28:31]
	v_mfma_f32_16x16x32_bf16 v[20:23], v[212:215], v[236:239], v[20:23]
	v_mfma_f32_16x16x32_bf16 v[12:15], v[204:207], v[244:247], v[12:15]
	v_mfma_f32_16x16x32_bf16 v[4:7], v[212:215], v[244:247], v[4:7]
	s_barrier
	s_setprio 0
	s_add_i32 s51, s51, 2
	s_add_u32 s18, s18, 0x100
	s_addc_u32 s19, s19, 0
	s_add_u32 s45, s45, 0x100
	s_addc_u32 s50, s50, 0
	s_cmp_gt_u32 s51, 29

; #define PG8_STAGE(bufoff, gbase, voff) do { _Pragma("unroll") for (int _i = 0; _i < 2; ++_i) \
;         __builtin_amdgcn_global_load_lds((const unsigned*)((const char*)(gbase) + (voff)[_i]), (PG8_LAS unsigned*)(lds + (bufoff) + ldsw + _i * 8192), 16, 0, 0); } while (0)
; #define PG8_LDA(dst, b, h) do { _Pragma("unroll") for (int m = 0; m < 4; ++m) _Pragma("unroll") for (int k = 0; k < 2; ++k) dst[m][k] = *(const PG8_LAS bf16x8*)(lds + PG8_SA(b, h) + aoff + m * 2048 + k * 1024); } while (0)
; #define PG8_LDB(dst, b, h) do { _Pragma("unroll") for (int n = 0; n < 2; ++n) _Pragma("unroll") for (int k = 0; k < 2; ++k) dst[n][k] = *(const PG8_LAS bf16x8*)(lds + PG8_SB(b, h) + boff + n * 2048 + k * 1024); } while (0)
; #define PG8_MMA(ai, bj, At, Bt) do { __builtin_amdgcn_s_setprio(1); _Pragma("unroll") for (int m = 0; m < 4; ++m) _Pragma("unroll") for (int n = 0; n < 2; ++n) _Pragma("unroll") for (int k = 0; k < 2; ++k) \
;         acc[ai][bj][m][n] = __builtin_amdgcn_mfma_f32_16x16x32_bf16(Bt[n][k], At[m][k], acc[ai][bj][m][n], 0, 0, 0); __builtin_amdgcn_s_setprio(0); } while (0)
; #define PG8_WAIT_V(n) asm volatile("s_waitcnt vmcnt(" #n ")" ::: "memory")
; #define PG8_WAIT_L(n) asm volatile("s_waitcnt lgkmcnt(" #n ")" ::: "memory")
; #define PG8_BAR __builtin_amdgcn_s_barrier()
; #define PG8_SCHED __builtin_amdgcn_sched_barrier(0)
; template <class Epi, class Sched, bool ALIGN_EPI = false, bool SP2 = false>
; __device__ __forceinline__ void gemm_phase(PG8_LAS unsigned char* lds, const Gemm g, const Sched& S, const Epi& E) {
;     ...
;             PG8_LDB(B0, 0, 0); PG8_LDB(B1, 0, 1); PG8_SCHED; PG8_LDA(At, 0, 0); PG8_STAGE(PG8_SA(1, 1), a1 + hstep, voffA);
;             PG8_WAIT_V(8); PG8_WAIT_L(0); PG8_BAR; PG8_MMA(0, 0, At, B0); PG8_MMA(0, 1, At, B1); PG8_BAR; PG8_SCHED;
;             PG8_LDA(At, 0, 1); PG8_STAGE(PG8_SB(0, 0), b2, voffB); PG8_STAGE(PG8_SB(0, 1), b2 + hstep, voffB); PG8_STAGE(PG8_SA(0, 0), a2, voffA);
;             PG8_WAIT_V(8); PG8_WAIT_L(0); PG8_BAR; PG8_MMA(1, 0, At, B0); PG8_MMA(1, 1, At, B1); PG8_BAR; PG8_SCHED;
.LBB0_166:
	s_add_u32 s51, s16, 0x100
	s_addc_u32 s56, s17, 0
	s_mov_b32 s57, -2
	s_waitcnt lgkmcnt(0)
	s_add_u32 s16, s14, 0x100
	s_addc_u32 s17, s15, 0
	s_add_i32 s63, 0, 0x10000
	s_cmpk_eq_i32 s57, 0x54
	s_cselect_b32 s21, s7, s17
	s_cselect_b32 s20, s6, s16
	s_cselect_b32 s19, s13, s56
	s_cselect_b32 s18, s12, s51
	s_add_i32 s64, 0, 0x14000
	v_add_u32_e32 v162, s63, v185
	v_add_u32_e32 v166, s64, v185
	ds_read_b128 v[132:135], v162
	ds_read_b128 v[136:139], v162 offset:1024
	ds_read_b128 v[158:161], v162 offset:2048
	ds_read_b128 v[162:165], v162 offset:3072
	ds_read_b128 v[188:191], v166
	ds_read_b128 v[192:195], v166 offset:1024
	ds_read_b128 v[196:199], v166 offset:2048
	ds_read_b128 v[200:203], v166 offset:3072
	s_add_i32 m0, s26, 0xc000
	ds_read_b128 v[204:207], v187
	ds_read_b128 v[208:211], v187 offset:1024
	ds_read_b128 v[212:215], v187 offset:2048
	ds_read_b128 v[216:219], v187 offset:3072
	ds_read_b128 v[220:223], v187 offset:4096
	ds_read_b128 v[224:227], v187 offset:5120
	ds_read_b128 v[228:231], v187 offset:6144
	ds_read_b128 v[232:235], v187 offset:7168
	global_load_lds_dwordx4 v154, s[14:15]
	s_add_i32 m0, s26, 0xe000
	s_nop 0
	global_load_lds_dwordx4 v156, s[14:15]
	s_waitcnt vmcnt(24)
	s_waitcnt lgkmcnt(0)
	s_setprio 1
	s_barrier
	v_mfma_f32_16x16x32_bf16 v[128:131], v[132:135], v[204:207], 0
	v_mfma_f32_16x16x32_bf16 v[124:127], v[158:161], v[204:207], 0
	v_mfma_f32_16x16x32_bf16 v[112:115], v[132:135], v[212:215], 0
	v_mfma_f32_16x16x32_bf16 v[108:111], v[158:161], v[212:215], 0
	v_mfma_f32_16x16x32_bf16 v[96:99], v[132:135], v[220:223], 0
	v_mfma_f32_16x16x32_bf16 v[92:95], v[158:161], v[220:223], 0
	v_mfma_f32_16x16x32_bf16 v[80:83], v[132:135], v[228:231], 0
	v_mfma_f32_16x16x32_bf16 v[76:79], v[158:161], v[228:231], 0
	v_mfma_f32_16x16x32_bf16 v[128:131], v[136:139], v[208:211], v[128:131]
	v_mfma_f32_16x16x32_bf16 v[124:127], v[162:165], v[208:211], v[124:127]
	v_mfma_f32_16x16x32_bf16 v[112:115], v[136:139], v[216:219], v[112:115]
	v_mfma_f32_16x16x32_bf16 v[108:111], v[162:165], v[216:219], v[108:111]
	v_mfma_f32_16x16x32_bf16 v[96:99], v[136:139], v[224:227], v[96:99]
	v_mfma_f32_16x16x32_bf16 v[92:95], v[162:165], v[224:227], v[92:95]
	v_mfma_f32_16x16x32_bf16 v[80:83], v[136:139], v[232:235], v[80:83]
	v_mfma_f32_16x16x32_bf16 v[76:79], v[162:165], v[232:235], v[76:79]
	v_mfma_f32_16x16x32_bf16 v[120:123], v[188:191], v[204:207], 0
	v_mfma_f32_16x16x32_bf16 v[116:119], v[196:199], v[204:207], 0
	v_mfma_f32_16x16x32_bf16 v[104:107], v[188:191], v[212:215], 0
	v_mfma_f32_16x16x32_bf16 v[100:103], v[196:199], v[212:215], 0
	v_mfma_f32_16x16x32_bf16 v[88:91], v[188:191], v[220:223], 0
	v_mfma_f32_16x16x32_bf16 v[84:87], v[196:199], v[220:223], 0
	v_mfma_f32_16x16x32_bf16 v[72:75], v[188:191], v[228:231], 0
	v_mfma_f32_16x16x32_bf16 v[68:71], v[196:199], v[228:231], 0
	v_mfma_f32_16x16x32_bf16 v[120:123], v[192:195], v[208:211], v[120:123]
	v_mfma_f32_16x16x32_bf16 v[116:119], v[200:203], v[208:211], v[116:119]
	v_mfma_f32_16x16x32_bf16 v[104:107], v[192:195], v[216:219], v[104:107]
	v_mfma_f32_16x16x32_bf16 v[100:103], v[200:203], v[216:219], v[100:103]
	v_mfma_f32_16x16x32_bf16 v[88:91], v[192:195], v[224:227], v[88:91]
	v_mfma_f32_16x16x32_bf16 v[84:87], v[200:203], v[224:227], v[84:87]
	v_mfma_f32_16x16x32_bf16 v[72:75], v[192:195], v[232:235], v[72:75]
	v_mfma_f32_16x16x32_bf16 v[68:71], v[200:203], v[232:235], v[68:71]
	s_barrier
	s_setprio 0
	s_add_i32 s14, s63, s25
	s_mov_b32 m0, s14
	ds_read_b128 v[204:207], v187 offset:16384
	ds_read_b128 v[208:211], v187 offset:17408
	ds_read_b128 v[212:215], v187 offset:18432
	ds_read_b128 v[216:219], v187 offset:19456
	ds_read_b128 v[220:223], v187 offset:20480
	ds_read_b128 v[224:227], v187 offset:21504
	ds_read_b128 v[228:231], v187 offset:22528
	ds_read_b128 v[232:235], v187 offset:23552
	global_load_lds_dwordx4 v2, s[18:19]
	s_add_i32 m0, s14, 0x2000
	s_add_u32 s14, s18, 0x160000
	v_lshl_add_u64 v[236:237], s[18:19], 0, v[152:153]
	s_addc_u32 s15, s19, 0
	s_add_i32 s63, s64, s25
	global_load_lds_dwordx4 v[236:237], off
	s_mov_b32 m0, s63
	s_nop 0
	global_load_lds_dwordx4 v2, s[14:15]
	s_add_i32 m0, s63, 0x2000
	s_nop 0
	global_load_lds_dwordx4 v152, s[14:15]
	s_mov_b32 m0, s26
	s_nop 0
	global_load_lds_dwordx4 v0, s[20:21]
	s_mov_b32 m0, s27
	s_nop 0
	global_load_lds_dwordx4 v150, s[20:21]
	s_waitcnt vmcnt(8)
	s_waitcnt lgkmcnt(0)
	s_setprio 1
	s_barrier
	v_mfma_f32_16x16x32_bf16 v[64:67], v[132:135], v[204:207], 0
	v_mfma_f32_16x16x32_bf16 v[60:63], v[158:161], v[204:207], 0
	v_mfma_f32_16x16x32_bf16 v[48:51], v[132:135], v[212:215], 0
	v_mfma_f32_16x16x32_bf16 v[44:47], v[158:161], v[212:215], 0
	v_mfma_f32_16x16x32_bf16 v[32:35], v[132:135], v[220:223], 0
	v_mfma_f32_16x16x32_bf16 v[28:31], v[158:161], v[220:223], 0
	v_mfma_f32_16x16x32_bf16 v[16:19], v[132:135], v[228:231], 0
	v_mfma_f32_16x16x32_bf16 v[12:15], v[158:161], v[228:231], 0
	v_mfma_f32_16x16x32_bf16 v[64:67], v[136:139], v[208:211], v[64:67]
	v_mfma_f32_16x16x32_bf16 v[60:63], v[162:165], v[208:211], v[60:63]
	v_mfma_f32_16x16x32_bf16 v[48:51], v[136:139], v[216:219], v[48:51]
	v_mfma_f32_16x16x32_bf16 v[44:47], v[162:165], v[216:219], v[44:47]
	v_mfma_f32_16x16x32_bf16 v[32:35], v[136:139], v[224:227], v[32:35]
	v_mfma_f32_16x16x32_bf16 v[28:31], v[162:165], v[224:227], v[28:31]
	v_mfma_f32_16x16x32_bf16 v[16:19], v[136:139], v[232:235], v[16:19]
	v_mfma_f32_16x16x32_bf16 v[12:15], v[162:165], v[232:235], v[12:15]
	v_mfma_f32_16x16x32_bf16 v[56:59], v[188:191], v[204:207], 0
	v_mfma_f32_16x16x32_bf16 v[52:55], v[196:199], v[204:207], 0
	v_mfma_f32_16x16x32_bf16 v[40:43], v[188:191], v[212:215], 0
	v_mfma_f32_16x16x32_bf16 v[36:39], v[196:199], v[212:215], 0
	v_mfma_f32_16x16x32_bf16 v[24:27], v[188:191], v[220:223], 0
	v_mfma_f32_16x16x32_bf16 v[20:23], v[196:199], v[220:223], 0
	v_mfma_f32_16x16x32_bf16 v[8:11], v[188:191], v[228:231], 0
	v_mfma_f32_16x16x32_bf16 v[4:7], v[196:199], v[228:231], 0
	v_mfma_f32_16x16x32_bf16 v[56:59], v[192:195], v[208:211], v[56:59]
	v_mfma_f32_16x16x32_bf16 v[52:55], v[200:203], v[208:211], v[52:55]
	v_mfma_f32_16x16x32_bf16 v[40:43], v[192:195], v[216:219], v[40:43]
	v_mfma_f32_16x16x32_bf16 v[36:39], v[200:203], v[216:219], v[36:39]
	v_mfma_f32_16x16x32_bf16 v[24:27], v[192:195], v[224:227], v[24:27]
	v_mfma_f32_16x16x32_bf16 v[20:23], v[200:203], v[224:227], v[20:23]
	v_mfma_f32_16x16x32_bf16 v[8:11], v[192:195], v[232:235], v[8:11]
	v_mfma_f32_16x16x32_bf16 v[4:7], v[200:203], v[232:235], v[4:7]
	s_barrier
; #define PG8_STAGE(bufoff, gbase, voff) do { _Pragma("unroll") for (int _i = 0; _i < 2; ++_i) \
;         __builtin_amdgcn_global_load_lds((const unsigned*)((const char*)(gbase) + (voff)[_i]), (PG8_LAS unsigned*)(lds + (bufoff) + ldsw + _i * 8192), 16, 0, 0); } while (0)
; #define PG8_LDA(dst, b, h) do { _Pragma("unroll") for (int m = 0; m < 4; ++m) _Pragma("unroll") for (int k = 0; k < 2; ++k) dst[m][k] = *(const PG8_LAS bf16x8*)(lds + PG8_SA(b, h) + aoff + m * 2048 + k * 1024); } while (0)
; #define PG8_LDB(dst, b, h) do { _Pragma("unroll") for (int n = 0; n < 2; ++n) _Pragma("unroll") for (int k = 0; k < 2; ++k) dst[n][k] = *(const PG8_LAS bf16x8*)(lds + PG8_SB(b, h) + boff + n * 2048 + k * 1024); } while (0)
; #define PG8_MMA(ai, bj, At, Bt) do { __builtin_amdgcn_s_setprio(1); _Pragma("unroll") for (int m = 0; m < 4; ++m) _Pragma("unroll") for (int n = 0; n < 2; ++n) _Pragma("unroll") for (int k = 0; k < 2; ++k) \
;         acc[ai][bj][m][n] = __builtin_amdgcn_mfma_f32_16x16x32_bf16(Bt[n][k], At[m][k], acc[ai][bj][m][n], 0, 0, 0); __builtin_amdgcn_s_setprio(0); } while (0)
; #define PG8_WAIT_V(n) asm volatile("s_waitcnt vmcnt(" #n ")" ::: "memory")
; #define PG8_WAIT_L(n) asm volatile("s_waitcnt lgkmcnt(" #n ")" ::: "memory")
; #define PG8_BAR __builtin_amdgcn_s_barrier()
; #define PG8_SCHED __builtin_amdgcn_sched_barrier(0)
; template <class Epi, class Sched, bool ALIGN_EPI = false, bool SP2 = false>
; __device__ __forceinline__ void gemm_phase(PG8_LAS unsigned char* lds, const Gemm g, const Sched& S, const Epi& E) {
;     ...
;             PG8_LDB(B0, 1, 0); PG8_LDB(B1, 1, 1); PG8_SCHED; PG8_LDA(At, 1, 0); PG8_STAGE(PG8_SA(0, 1), a2 + hstep, voffA);
;             PG8_WAIT_V(8); PG8_WAIT_L(0); PG8_BAR; PG8_MMA(0, 0, At, B0); PG8_MMA(0, 1, At, B1); PG8_BAR; PG8_SCHED;
;             PG8_LDA(At, 1, 1); PG8_STAGE(PG8_SB(1, 0), b3, voffB); PG8_STAGE(PG8_SB(1, 1), b3 + hstep, voffB); PG8_STAGE(PG8_SA(1, 0), a3, voffA);
;             PG8_WAIT_V(8); PG8_WAIT_L(0); PG8_BAR; PG8_MMA(1, 0, At, B0); PG8_MMA(1, 1, At, B1); PG8_BAR; PG8_SCHED;
	s_setprio 0
	s_add_i32 s63, 0, 0x18000
	s_add_i32 s64, 0, 0x1c000
	v_add_u32_e32 v162, s63, v185
	v_add_u32_e32 v200, s64, v185
	ds_read_b128 v[132:135], v162
	ds_read_b128 v[136:139], v162 offset:1024
	ds_read_b128 v[158:161], v162 offset:2048
	ds_read_b128 v[162:165], v162 offset:3072
	ds_read_b128 v[188:191], v200
	ds_read_b128 v[192:195], v200 offset:1024
	ds_read_b128 v[196:199], v200 offset:2048
	ds_read_b128 v[200:203], v200 offset:3072
	s_add_u32 s14, s20, 0x160000
	s_addc_u32 s15, s21, 0
	s_mov_b32 m0, s28
	ds_read_b128 v[204:207], v187 offset:32768
	ds_read_b128 v[208:211], v187 offset:33792
	ds_read_b128 v[212:215], v187 offset:34816
	ds_read_b128 v[216:219], v187 offset:35840
	ds_read_b128 v[220:223], v187 offset:36864
	ds_read_b128 v[224:227], v187 offset:37888
	ds_read_b128 v[228:231], v187 offset:38912
	ds_read_b128 v[232:235], v187 offset:39936
	global_load_lds_dwordx4 v0, s[14:15]
	s_mov_b32 m0, s29
	s_nop 0
	global_load_lds_dwordx4 v150, s[14:15]
	s_waitcnt vmcnt(8)
	s_waitcnt lgkmcnt(0)
	s_setprio 1
	s_barrier
	v_mfma_f32_16x16x32_bf16 v[128:131], v[132:135], v[204:207], v[128:131]
	v_mfma_f32_16x16x32_bf16 v[124:127], v[158:161], v[204:207], v[124:127]
	v_mfma_f32_16x16x32_bf16 v[112:115], v[132:135], v[212:215], v[112:115]
	v_mfma_f32_16x16x32_bf16 v[108:111], v[158:161], v[212:215], v[108:111]
	v_mfma_f32_16x16x32_bf16 v[96:99], v[132:135], v[220:223], v[96:99]
	v_mfma_f32_16x16x32_bf16 v[92:95], v[158:161], v[220:223], v[92:95]
	v_mfma_f32_16x16x32_bf16 v[80:83], v[132:135], v[228:231], v[80:83]
	v_mfma_f32_16x16x32_bf16 v[76:79], v[158:161], v[228:231], v[76:79]
	v_mfma_f32_16x16x32_bf16 v[128:131], v[136:139], v[208:211], v[128:131]
	v_mfma_f32_16x16x32_bf16 v[124:127], v[162:165], v[208:211], v[124:127]
	v_mfma_f32_16x16x32_bf16 v[112:115], v[136:139], v[216:219], v[112:115]
	v_mfma_f32_16x16x32_bf16 v[108:111], v[162:165], v[216:219], v[108:111]
	v_mfma_f32_16x16x32_bf16 v[96:99], v[136:139], v[224:227], v[96:99]
	v_mfma_f32_16x16x32_bf16 v[92:95], v[162:165], v[224:227], v[92:95]
	v_mfma_f32_16x16x32_bf16 v[80:83], v[136:139], v[232:235], v[80:83]
	v_mfma_f32_16x16x32_bf16 v[76:79], v[162:165], v[232:235], v[76:79]
	v_mfma_f32_16x16x32_bf16 v[120:123], v[188:191], v[204:207], v[120:123]
	v_mfma_f32_16x16x32_bf16 v[116:119], v[196:199], v[204:207], v[116:119]
	v_mfma_f32_16x16x32_bf16 v[104:107], v[188:191], v[212:215], v[104:107]
	v_mfma_f32_16x16x32_bf16 v[100:103], v[196:199], v[212:215], v[100:103]
	v_mfma_f32_16x16x32_bf16 v[88:91], v[188:191], v[220:223], v[88:91]
	v_mfma_f32_16x16x32_bf16 v[84:87], v[196:199], v[220:223], v[84:87]
	v_mfma_f32_16x16x32_bf16 v[72:75], v[188:191], v[228:231], v[72:75]
	v_mfma_f32_16x16x32_bf16 v[68:71], v[196:199], v[228:231], v[68:71]
	v_mfma_f32_16x16x32_bf16 v[120:123], v[192:195], v[208:211], v[120:123]
	v_mfma_f32_16x16x32_bf16 v[116:119], v[200:203], v[208:211], v[116:119]
	v_mfma_f32_16x16x32_bf16 v[104:107], v[192:195], v[216:219], v[104:107]
	v_mfma_f32_16x16x32_bf16 v[100:103], v[200:203], v[216:219], v[100:103]
	v_mfma_f32_16x16x32_bf16 v[88:91], v[192:195], v[224:227], v[88:91]
	v_mfma_f32_16x16x32_bf16 v[84:87], v[200:203], v[224:227], v[84:87]
	v_mfma_f32_16x16x32_bf16 v[72:75], v[192:195], v[232:235], v[72:75]
	v_mfma_f32_16x16x32_bf16 v[68:71], v[200:203], v[232:235], v[68:71]
	s_barrier
	s_setprio 0
	s_add_i32 s14, s63, s25
	s_mov_b32 m0, s14
	ds_read_b128 v[204:207], v187 offset:49152
	ds_read_b128 v[208:211], v187 offset:50176
	ds_read_b128 v[212:215], v187 offset:51200
	ds_read_b128 v[216:219], v187 offset:52224
	ds_read_b128 v[220:223], v187 offset:53248
	ds_read_b128 v[224:227], v187 offset:54272
	ds_read_b128 v[228:231], v187 offset:55296
	ds_read_b128 v[232:235], v187 offset:56320
	s_add_u32 vcc_lo, s18, 0x80
	s_addc_u32 vcc_hi, s19, 0
	global_load_lds_dwordx4 v2, vcc
	s_add_i32 m0, s14, 0x2000
	s_add_u32 s14, s18, 0x160080
	v_lshl_add_u64 v[166:167], v[236:237], 0, s[36:37]
	s_addc_u32 s15, s19, 0
	s_add_i32 s18, s64, s25
	global_load_lds_dwordx4 v[166:167], off
	s_mov_b32 m0, s18
	s_nop 0
	global_load_lds_dwordx4 v2, s[14:15]
	v_lshl_add_u64 v[166:167], s[14:15], 0, v[152:153]
	s_add_i32 m0, s18, 0x2000
	s_nop 0
	global_load_lds_dwordx4 v[166:167], off
	s_mov_b32 m0, s30
	s_nop 0
	s_add_u32 vcc_lo, s20, 0x80
	s_addc_u32 vcc_hi, s21, 0
	global_load_lds_dwordx4 v0, vcc
	s_mov_b32 m0, s31
	s_nop 0
	s_add_u32 vcc_lo, s20, 0x80
	s_addc_u32 vcc_hi, s21, 0
	global_load_lds_dwordx4 v150, vcc
	s_waitcnt vmcnt(8)
	s_waitcnt lgkmcnt(0)
	s_setprio 1
	s_barrier
	v_mfma_f32_16x16x32_bf16 v[64:67], v[132:135], v[204:207], v[64:67]
	v_mfma_f32_16x16x32_bf16 v[60:63], v[158:161], v[204:207], v[60:63]
	v_mfma_f32_16x16x32_bf16 v[48:51], v[132:135], v[212:215], v[48:51]
	v_mfma_f32_16x16x32_bf16 v[44:47], v[158:161], v[212:215], v[44:47]
	v_mfma_f32_16x16x32_bf16 v[32:35], v[132:135], v[220:223], v[32:35]
	v_mfma_f32_16x16x32_bf16 v[28:31], v[158:161], v[220:223], v[28:31]
	v_mfma_f32_16x16x32_bf16 v[16:19], v[132:135], v[228:231], v[16:19]
	v_mfma_f32_16x16x32_bf16 v[12:15], v[158:161], v[228:231], v[12:15]
	v_mfma_f32_16x16x32_bf16 v[64:67], v[136:139], v[208:211], v[64:67]
	v_mfma_f32_16x16x32_bf16 v[60:63], v[162:165], v[208:211], v[60:63]
	v_mfma_f32_16x16x32_bf16 v[48:51], v[136:139], v[216:219], v[48:51]
	v_mfma_f32_16x16x32_bf16 v[44:47], v[162:165], v[216:219], v[44:47]
	v_mfma_f32_16x16x32_bf16 v[32:35], v[136:139], v[224:227], v[32:35]
	v_mfma_f32_16x16x32_bf16 v[28:31], v[162:165], v[224:227], v[28:31]
	v_mfma_f32_16x16x32_bf16 v[16:19], v[136:139], v[232:235], v[16:19]
	v_mfma_f32_16x16x32_bf16 v[12:15], v[162:165], v[232:235], v[12:15]
	v_mfma_f32_16x16x32_bf16 v[56:59], v[188:191], v[204:207], v[56:59]
	v_mfma_f32_16x16x32_bf16 v[52:55], v[196:199], v[204:207], v[52:55]
	v_mfma_f32_16x16x32_bf16 v[40:43], v[188:191], v[212:215], v[40:43]
	v_mfma_f32_16x16x32_bf16 v[36:39], v[196:199], v[212:215], v[36:39]
	v_mfma_f32_16x16x32_bf16 v[24:27], v[188:191], v[220:223], v[24:27]
	v_mfma_f32_16x16x32_bf16 v[20:23], v[196:199], v[220:223], v[20:23]
	v_mfma_f32_16x16x32_bf16 v[8:11], v[188:191], v[228:231], v[8:11]
	v_mfma_f32_16x16x32_bf16 v[4:7], v[196:199], v[228:231], v[4:7]
	v_mfma_f32_16x16x32_bf16 v[56:59], v[192:195], v[208:211], v[56:59]
	v_mfma_f32_16x16x32_bf16 v[52:55], v[200:203], v[208:211], v[52:55]
	v_mfma_f32_16x16x32_bf16 v[40:43], v[192:195], v[216:219], v[40:43]
	v_mfma_f32_16x16x32_bf16 v[36:39], v[200:203], v[216:219], v[36:39]
	v_mfma_f32_16x16x32_bf16 v[24:27], v[192:195], v[224:227], v[24:27]
	v_mfma_f32_16x16x32_bf16 v[20:23], v[200:203], v[224:227], v[20:23]
	v_mfma_f32_16x16x32_bf16 v[8:11], v[192:195], v[232:235], v[8:11]
	v_mfma_f32_16x16x32_bf16 v[4:7], v[200:203], v[232:235], v[4:7]
	s_barrier
	s_setprio 0
	s_add_i32 s57, s57, 2
	s_add_u32 s51, s51, 0x100
	s_addc_u32 s56, s56, 0
	s_cmpk_gt_u32 s57, 0x55
	s_mov_b64 s[14:15], s[16:17]

; #define PG8_STAGE(bufoff, gbase, voff) do { _Pragma("unroll") for (int _i = 0; _i < 2; ++_i) \
;         __builtin_amdgcn_global_load_lds((const unsigned*)((const char*)(gbase) + (voff)[_i]), (PG8_LAS unsigned*)(lds + (bufoff) + ldsw + _i * 8192), 16, 0, 0); } while (0)
; #define PG8_LDA(dst, b, h) do { _Pragma("unroll") for (int m = 0; m < 4; ++m) _Pragma("unroll") for (int k = 0; k < 2; ++k) dst[m][k] = *(const PG8_LAS bf16x8*)(lds + PG8_SA(b, h) + aoff + m * 2048 + k * 1024); } while (0)
; #define PG8_LDB(dst, b, h) do { _Pragma("unroll") for (int n = 0; n < 2; ++n) _Pragma("unroll") for (int k = 0; k < 2; ++k) dst[n][k] = *(const PG8_LAS bf16x8*)(lds + PG8_SB(b, h) + boff + n * 2048 + k * 1024); } while (0)
; #define PG8_MMA(ai, bj, At, Bt) do { __builtin_amdgcn_s_setprio(1); _Pragma("unroll") for (int m = 0; m < 4; ++m) _Pragma("unroll") for (int n = 0; n < 2; ++n) _Pragma("unroll") for (int k = 0; k < 2; ++k) \
;         acc[ai][bj][m][n] = __builtin_amdgcn_mfma_f32_16x16x32_bf16(Bt[n][k], At[m][k], acc[ai][bj][m][n], 0, 0, 0); __builtin_amdgcn_s_setprio(0); } while (0)
; #define PG8_WAIT_V(n) asm volatile("s_waitcnt vmcnt(" #n ")" ::: "memory")
; #define PG8_WAIT_L(n) asm volatile("s_waitcnt lgkmcnt(" #n ")" ::: "memory")
; #define PG8_BAR __builtin_amdgcn_s_barrier()
; #define PG8_SCHED __builtin_amdgcn_sched_barrier(0)
; template <class Epi, class Sched, bool ALIGN_EPI = false, bool SP2 = false>
; __device__ __forceinline__ void gemm_phase(PG8_LAS unsigned char* lds, const Gemm g, const Sched& S, const Epi& E) {
;     ...
;             PG8_LDB(B0, 0, 0); PG8_LDB(B1, 0, 1); PG8_SCHED; PG8_LDA(At, 0, 0); PG8_STAGE(PG8_SA(1, 1), a1 + hstep, voffA);
;             PG8_WAIT_V(8); PG8_WAIT_L(0); PG8_BAR; PG8_MMA(0, 0, At, B0); PG8_MMA(0, 1, At, B1); PG8_BAR; PG8_SCHED;
;             PG8_LDA(At, 0, 1); PG8_STAGE(PG8_SB(0, 0), b2, voffB); PG8_STAGE(PG8_SB(0, 1), b2 + hstep, voffB); PG8_STAGE(PG8_SA(0, 0), a2, voffA);
;             PG8_WAIT_V(8); PG8_WAIT_L(0); PG8_BAR; PG8_MMA(1, 0, At, B0); PG8_MMA(1, 1, At, B1); PG8_BAR; PG8_SCHED;
.LBB0_250:
	s_ashr_i32 s11, s10, 31
	s_lshl_b64 s[12:13], s[10:11], 20
	s_add_u32 s12, s46, s12
	s_addc_u32 s13, s47, s13
	s_and_b64 s[14:15], s[2:3], exec
	s_cselect_b32 s11, s13, s19
	s_cselect_b32 s45, s12, s18
	s_ashr_i32 s7, s6, 31
	s_lshl_b64 s[14:15], s[6:7], 20
	s_add_u32 s14, s25, s14
	s_addc_u32 s15, s26, s15
	s_and_b64 s[22:23], s[2:3], exec
	s_cselect_b32 s7, s15, s21
	s_cselect_b32 s50, s14, s20
	s_add_u32 s18, s18, 0x80080
	s_addc_u32 s19, s19, 0
	s_add_u32 s51, s20, 0x100
	s_addc_u32 s56, s21, 0
	s_mov_b32 s57, -2
	s_add_u32 s20, s18, 0xfff80080
	s_addc_u32 s21, s19, -1
	s_add_i32 s63, 0, 0x10000
	s_cmp_eq_u32 s57, 28
	s_cselect_b32 s23, s11, s21
	s_cselect_b32 s22, s45, s20
	v_add_u32_e32 v151, s63, v156
	s_cselect_b32 s21, s7, s56
	s_cselect_b32 s20, s50, s51
	s_add_i32 s66, 0, 0x14000
	ds_read_b128 v[184:187], v151
	ds_read_b128 v[188:191], v151 offset:1024
	ds_read_b128 v[192:195], v151 offset:2048
	ds_read_b128 v[196:199], v151 offset:3072
	v_add_u32_e32 v151, s66, v156
	ds_read_b128 v[200:203], v151
	ds_read_b128 v[204:207], v151 offset:1024
	ds_read_b128 v[208:211], v151 offset:2048
	ds_read_b128 v[212:215], v151 offset:3072
	s_add_i32 m0, s17, 0xc000
	ds_read_b128 v[216:219], v160
	ds_read_b128 v[220:223], v160 offset:1024
	ds_read_b128 v[224:227], v160 offset:2048
	ds_read_b128 v[228:231], v160 offset:3072
	ds_read_b128 v[232:235], v160 offset:4096
	ds_read_b128 v[236:239], v160 offset:5120
	ds_read_b128 v[240:243], v160 offset:6144
	ds_read_b128 v[244:247], v160 offset:7168
	global_load_lds_dwordx4 v136, s[18:19]
	s_add_i32 m0, s17, 0xe000
	s_nop 0
	global_load_lds_dwordx4 v138, s[18:19]
	s_waitcnt vmcnt(32)
	s_waitcnt lgkmcnt(0)
	s_setprio 1
	s_barrier
	v_mfma_f32_16x16x32_bf16 v[128:131], v[184:187], v[216:219], 0
	v_mfma_f32_16x16x32_bf16 v[124:127], v[192:195], v[216:219], 0
	v_mfma_f32_16x16x32_bf16 v[112:115], v[184:187], v[224:227], 0
	v_mfma_f32_16x16x32_bf16 v[108:111], v[192:195], v[224:227], 0
	v_mfma_f32_16x16x32_bf16 v[96:99], v[184:187], v[232:235], 0
	v_mfma_f32_16x16x32_bf16 v[92:95], v[192:195], v[232:235], 0
	v_mfma_f32_16x16x32_bf16 v[80:83], v[184:187], v[240:243], 0
	v_mfma_f32_16x16x32_bf16 v[76:79], v[192:195], v[240:243], 0
	v_mfma_f32_16x16x32_bf16 v[128:131], v[188:191], v[220:223], v[128:131]
	v_mfma_f32_16x16x32_bf16 v[124:127], v[196:199], v[220:223], v[124:127]
	v_mfma_f32_16x16x32_bf16 v[112:115], v[188:191], v[228:231], v[112:115]
	v_mfma_f32_16x16x32_bf16 v[108:111], v[196:199], v[228:231], v[108:111]
	v_mfma_f32_16x16x32_bf16 v[96:99], v[188:191], v[236:239], v[96:99]
	v_mfma_f32_16x16x32_bf16 v[92:95], v[196:199], v[236:239], v[92:95]
	v_mfma_f32_16x16x32_bf16 v[80:83], v[188:191], v[244:247], v[80:83]
	v_mfma_f32_16x16x32_bf16 v[76:79], v[196:199], v[244:247], v[76:79]
	v_mfma_f32_16x16x32_bf16 v[120:123], v[200:203], v[216:219], 0
	v_mfma_f32_16x16x32_bf16 v[116:119], v[208:211], v[216:219], 0
	v_mfma_f32_16x16x32_bf16 v[104:107], v[200:203], v[224:227], 0
	v_mfma_f32_16x16x32_bf16 v[100:103], v[208:211], v[224:227], 0
	v_mfma_f32_16x16x32_bf16 v[88:91], v[200:203], v[232:235], 0
	v_mfma_f32_16x16x32_bf16 v[84:87], v[208:211], v[232:235], 0
	v_mfma_f32_16x16x32_bf16 v[72:75], v[200:203], v[240:243], 0
	v_mfma_f32_16x16x32_bf16 v[68:71], v[208:211], v[240:243], 0
	v_mfma_f32_16x16x32_bf16 v[120:123], v[204:207], v[220:223], v[120:123]
	v_mfma_f32_16x16x32_bf16 v[116:119], v[212:215], v[220:223], v[116:119]
	v_mfma_f32_16x16x32_bf16 v[104:107], v[204:207], v[228:231], v[104:107]
	v_mfma_f32_16x16x32_bf16 v[100:103], v[212:215], v[228:231], v[100:103]
	v_mfma_f32_16x16x32_bf16 v[88:91], v[204:207], v[236:239], v[88:91]
	v_mfma_f32_16x16x32_bf16 v[84:87], v[212:215], v[236:239], v[84:87]
	v_mfma_f32_16x16x32_bf16 v[72:75], v[204:207], v[244:247], v[72:75]
	v_mfma_f32_16x16x32_bf16 v[68:71], v[212:215], v[244:247], v[68:71]
	s_barrier
	s_setprio 0
	s_add_i32 s63, s63, s27
	s_mov_b32 m0, s63
	ds_read_b128 v[216:219], v160 offset:16384
	ds_read_b128 v[220:223], v160 offset:17408
	ds_read_b128 v[224:227], v160 offset:18432
	ds_read_b128 v[228:231], v160 offset:19456
	ds_read_b128 v[232:235], v160 offset:20480
	ds_read_b128 v[236:239], v160 offset:21504
	ds_read_b128 v[240:243], v160 offset:22528
	ds_read_b128 v[244:247], v160 offset:23552
	global_load_lds_dwordx4 v2, s[20:21]
	s_add_i32 m0, s63, 0x2000
	s_add_u32 s64, s20, 0x80000
	s_addc_u32 s65, s21, 0
	s_add_i32 s63, s66, s27
	global_load_lds_dwordx4 v0, s[20:21]
	s_mov_b32 m0, s63
	v_lshl_add_u64 v[250:251], s[22:23], 0, v[132:133]
	global_load_lds_dwordx4 v2, s[64:65]
	s_add_i32 m0, s63, 0x2000
	s_nop 0
	global_load_lds_dwordx4 v0, s[64:65]
	v_lshl_add_u64 v[248:249], s[22:23], 0, v[134:135]
	s_mov_b32 m0, s17
	s_nop 0
	global_load_lds_dwordx4 v[248:249], off
	s_mov_b32 m0, s29
	s_nop 0
	global_load_lds_dwordx4 v[250:251], off
	s_waitcnt vmcnt(8)
	s_waitcnt lgkmcnt(0)
	s_setprio 1
	s_barrier
; #define PG8_STAGE(bufoff, gbase, voff) do { _Pragma("unroll") for (int _i = 0; _i < 2; ++_i) \
;         __builtin_amdgcn_global_load_lds((const unsigned*)((const char*)(gbase) + (voff)[_i]), (PG8_LAS unsigned*)(lds + (bufoff) + ldsw + _i * 8192), 16, 0, 0); } while (0)
; #define PG8_LDA(dst, b, h) do { _Pragma("unroll") for (int m = 0; m < 4; ++m) _Pragma("unroll") for (int k = 0; k < 2; ++k) dst[m][k] = *(const PG8_LAS bf16x8*)(lds + PG8_SA(b, h) + aoff + m * 2048 + k * 1024); } while (0)
; #define PG8_LDB(dst, b, h) do { _Pragma("unroll") for (int n = 0; n < 2; ++n) _Pragma("unroll") for (int k = 0; k < 2; ++k) dst[n][k] = *(const PG8_LAS bf16x8*)(lds + PG8_SB(b, h) + boff + n * 2048 + k * 1024); } while (0)
; #define PG8_MMA(ai, bj, At, Bt) do { __builtin_amdgcn_s_setprio(1); _Pragma("unroll") for (int m = 0; m < 4; ++m) _Pragma("unroll") for (int n = 0; n < 2; ++n) _Pragma("unroll") for (int k = 0; k < 2; ++k) \
;         acc[ai][bj][m][n] = __builtin_amdgcn_mfma_f32_16x16x32_bf16(Bt[n][k], At[m][k], acc[ai][bj][m][n], 0, 0, 0); __builtin_amdgcn_s_setprio(0); } while (0)
; #define PG8_WAIT_V(n) asm volatile("s_waitcnt vmcnt(" #n ")" ::: "memory")
; #define PG8_WAIT_L(n) asm volatile("s_waitcnt lgkmcnt(" #n ")" ::: "memory")
; #define PG8_BAR __builtin_amdgcn_s_barrier()
; #define PG8_SCHED __builtin_amdgcn_sched_barrier(0)
; template <class Epi, class Sched, bool ALIGN_EPI = false, bool SP2 = false>
; __device__ __forceinline__ void gemm_phase(PG8_LAS unsigned char* lds, const Gemm g, const Sched& S, const Epi& E) {
;     ...
;             PG8_WAIT_V(8); PG8_WAIT_L(0); PG8_BAR; PG8_MMA(1, 0, At, B0); PG8_MMA(1, 1, At, B1); PG8_BAR; PG8_SCHED;
;             PG8_LDB(B0, 1, 0); PG8_LDB(B1, 1, 1); PG8_SCHED; PG8_LDA(At, 1, 0); PG8_STAGE(PG8_SA(0, 1), a2 + hstep, voffA);
;             PG8_WAIT_V(8); PG8_WAIT_L(0); PG8_BAR; PG8_MMA(0, 0, At, B0); PG8_MMA(0, 1, At, B1); PG8_BAR; PG8_SCHED;
	v_mfma_f32_16x16x32_bf16 v[64:67], v[184:187], v[216:219], 0
	v_mfma_f32_16x16x32_bf16 v[60:63], v[192:195], v[216:219], 0
	v_mfma_f32_16x16x32_bf16 v[48:51], v[184:187], v[224:227], 0
	v_mfma_f32_16x16x32_bf16 v[44:47], v[192:195], v[224:227], 0
	v_mfma_f32_16x16x32_bf16 v[32:35], v[184:187], v[232:235], 0
	v_mfma_f32_16x16x32_bf16 v[28:31], v[192:195], v[232:235], 0
	v_mfma_f32_16x16x32_bf16 v[16:19], v[184:187], v[240:243], 0
	v_mfma_f32_16x16x32_bf16 v[12:15], v[192:195], v[240:243], 0
	v_mfma_f32_16x16x32_bf16 v[64:67], v[188:191], v[220:223], v[64:67]
	v_mfma_f32_16x16x32_bf16 v[60:63], v[196:199], v[220:223], v[60:63]
	v_mfma_f32_16x16x32_bf16 v[48:51], v[188:191], v[228:231], v[48:51]
	v_mfma_f32_16x16x32_bf16 v[44:47], v[196:199], v[228:231], v[44:47]
	v_mfma_f32_16x16x32_bf16 v[32:35], v[188:191], v[236:239], v[32:35]
	v_mfma_f32_16x16x32_bf16 v[28:31], v[196:199], v[236:239], v[28:31]
	v_mfma_f32_16x16x32_bf16 v[16:19], v[188:191], v[244:247], v[16:19]
	v_mfma_f32_16x16x32_bf16 v[12:15], v[196:199], v[244:247], v[12:15]
	v_mfma_f32_16x16x32_bf16 v[56:59], v[200:203], v[216:219], 0
	v_mfma_f32_16x16x32_bf16 v[52:55], v[208:211], v[216:219], 0
	v_mfma_f32_16x16x32_bf16 v[40:43], v[200:203], v[224:227], 0
	v_mfma_f32_16x16x32_bf16 v[36:39], v[208:211], v[224:227], 0
	v_mfma_f32_16x16x32_bf16 v[24:27], v[200:203], v[232:235], 0
	v_mfma_f32_16x16x32_bf16 v[20:23], v[208:211], v[232:235], 0
	v_mfma_f32_16x16x32_bf16 v[8:11], v[200:203], v[240:243], 0
	v_mfma_f32_16x16x32_bf16 v[4:7], v[208:211], v[240:243], 0
	v_mfma_f32_16x16x32_bf16 v[56:59], v[204:207], v[220:223], v[56:59]
	v_mfma_f32_16x16x32_bf16 v[52:55], v[212:215], v[220:223], v[52:55]
	v_mfma_f32_16x16x32_bf16 v[40:43], v[204:207], v[228:231], v[40:43]
	v_mfma_f32_16x16x32_bf16 v[36:39], v[212:215], v[228:231], v[36:39]
	v_mfma_f32_16x16x32_bf16 v[24:27], v[204:207], v[236:239], v[24:27]
	v_mfma_f32_16x16x32_bf16 v[20:23], v[212:215], v[236:239], v[20:23]
	v_mfma_f32_16x16x32_bf16 v[8:11], v[204:207], v[244:247], v[8:11]
	v_mfma_f32_16x16x32_bf16 v[4:7], v[212:215], v[244:247], v[4:7]
	s_barrier
	s_setprio 0
	s_add_i32 s63, 0, 0x18000
	v_add_u32_e32 v151, s63, v156
	s_add_i32 s64, 0, 0x1c000
	ds_read_b128 v[184:187], v151
	ds_read_b128 v[188:191], v151 offset:1024
	ds_read_b128 v[192:195], v151 offset:2048
	ds_read_b128 v[196:199], v151 offset:3072
	v_add_u32_e32 v151, s64, v156
	ds_read_b128 v[200:203], v151
	ds_read_b128 v[204:207], v151 offset:1024
	ds_read_b128 v[208:211], v151 offset:2048
	ds_read_b128 v[212:215], v151 offset:3072
	s_add_u32 s22, s22, 0x80000
	s_addc_u32 s23, s23, 0
	s_mov_b32 m0, s30
	ds_read_b128 v[216:219], v160 offset:32768
	ds_read_b128 v[220:223], v160 offset:33792
	ds_read_b128 v[224:227], v160 offset:34816
	ds_read_b128 v[228:231], v160 offset:35840
	ds_read_b128 v[232:235], v160 offset:36864
	ds_read_b128 v[236:239], v160 offset:37888
	ds_read_b128 v[240:243], v160 offset:38912
	ds_read_b128 v[244:247], v160 offset:39936
	global_load_lds_dwordx4 v134, s[22:23]
	s_mov_b32 m0, s31
	s_nop 0
	global_load_lds_dwordx4 v132, s[22:23]
	s_waitcnt vmcnt(8)
	s_waitcnt lgkmcnt(0)
	s_setprio 1
	s_barrier
	v_mfma_f32_16x16x32_bf16 v[128:131], v[184:187], v[216:219], v[128:131]
	v_mfma_f32_16x16x32_bf16 v[124:127], v[192:195], v[216:219], v[124:127]
	v_mfma_f32_16x16x32_bf16 v[112:115], v[184:187], v[224:227], v[112:115]
	v_mfma_f32_16x16x32_bf16 v[108:111], v[192:195], v[224:227], v[108:111]
	v_mfma_f32_16x16x32_bf16 v[96:99], v[184:187], v[232:235], v[96:99]
	v_mfma_f32_16x16x32_bf16 v[92:95], v[192:195], v[232:235], v[92:95]
	v_mfma_f32_16x16x32_bf16 v[80:83], v[184:187], v[240:243], v[80:83]
	v_mfma_f32_16x16x32_bf16 v[76:79], v[192:195], v[240:243], v[76:79]
	v_mfma_f32_16x16x32_bf16 v[128:131], v[188:191], v[220:223], v[128:131]
	v_mfma_f32_16x16x32_bf16 v[124:127], v[196:199], v[220:223], v[124:127]
	v_mfma_f32_16x16x32_bf16 v[112:115], v[188:191], v[228:231], v[112:115]
	v_mfma_f32_16x16x32_bf16 v[108:111], v[196:199], v[228:231], v[108:111]
	v_mfma_f32_16x16x32_bf16 v[96:99], v[188:191], v[236:239], v[96:99]
	v_mfma_f32_16x16x32_bf16 v[92:95], v[196:199], v[236:239], v[92:95]
	v_mfma_f32_16x16x32_bf16 v[80:83], v[188:191], v[244:247], v[80:83]
	v_mfma_f32_16x16x32_bf16 v[76:79], v[196:199], v[244:247], v[76:79]
	v_mfma_f32_16x16x32_bf16 v[120:123], v[200:203], v[216:219], v[120:123]
	v_mfma_f32_16x16x32_bf16 v[116:119], v[208:211], v[216:219], v[116:119]
	v_mfma_f32_16x16x32_bf16 v[104:107], v[200:203], v[224:227], v[104:107]
	v_mfma_f32_16x16x32_bf16 v[100:103], v[208:211], v[224:227], v[100:103]
	v_mfma_f32_16x16x32_bf16 v[88:91], v[200:203], v[232:235], v[88:91]
	v_mfma_f32_16x16x32_bf16 v[84:87], v[208:211], v[232:235], v[84:87]
	v_mfma_f32_16x16x32_bf16 v[72:75], v[200:203], v[240:243], v[72:75]
	v_mfma_f32_16x16x32_bf16 v[68:71], v[208:211], v[240:243], v[68:71]
	v_mfma_f32_16x16x32_bf16 v[120:123], v[204:207], v[220:223], v[120:123]
	v_mfma_f32_16x16x32_bf16 v[116:119], v[212:215], v[220:223], v[116:119]
	v_mfma_f32_16x16x32_bf16 v[104:107], v[204:207], v[228:231], v[104:107]
	v_mfma_f32_16x16x32_bf16 v[100:103], v[212:215], v[228:231], v[100:103]
	v_mfma_f32_16x16x32_bf16 v[88:91], v[204:207], v[236:239], v[88:91]
	v_mfma_f32_16x16x32_bf16 v[84:87], v[212:215], v[236:239], v[84:87]
	v_mfma_f32_16x16x32_bf16 v[72:75], v[204:207], v[244:247], v[72:75]
	v_mfma_f32_16x16x32_bf16 v[68:71], v[212:215], v[244:247], v[68:71]
	s_barrier
; #define PG8_STAGE(bufoff, gbase, voff) do { _Pragma("unroll") for (int _i = 0; _i < 2; ++_i) \
;         __builtin_amdgcn_global_load_lds((const unsigned*)((const char*)(gbase) + (voff)[_i]), (PG8_LAS unsigned*)(lds + (bufoff) + ldsw + _i * 8192), 16, 0, 0); } while (0)
; #define PG8_LDA(dst, b, h) do { _Pragma("unroll") for (int m = 0; m < 4; ++m) _Pragma("unroll") for (int k = 0; k < 2; ++k) dst[m][k] = *(const PG8_LAS bf16x8*)(lds + PG8_SA(b, h) + aoff + m * 2048 + k * 1024); } while (0)
; #define PG8_MMA(ai, bj, At, Bt) do { __builtin_amdgcn_s_setprio(1); _Pragma("unroll") for (int m = 0; m < 4; ++m) _Pragma("unroll") for (int n = 0; n < 2; ++n) _Pragma("unroll") for (int k = 0; k < 2; ++k) \
;         acc[ai][bj][m][n] = __builtin_amdgcn_mfma_f32_16x16x32_bf16(Bt[n][k], At[m][k], acc[ai][bj][m][n], 0, 0, 0); __builtin_amdgcn_s_setprio(0); } while (0)
; #define PG8_WAIT_V(n) asm volatile("s_waitcnt vmcnt(" #n ")" ::: "memory")
; #define PG8_WAIT_L(n) asm volatile("s_waitcnt lgkmcnt(" #n ")" ::: "memory")
; #define PG8_BAR __builtin_amdgcn_s_barrier()
; #define PG8_SCHED __builtin_amdgcn_sched_barrier(0)
; template <class Epi, class Sched, bool ALIGN_EPI = false, bool SP2 = false>
; __device__ __forceinline__ void gemm_phase(PG8_LAS unsigned char* lds, const Gemm g, const Sched& S, const Epi& E) {
;     ...
;             PG8_LDA(At, 1, 1); PG8_STAGE(PG8_SB(1, 0), b3, voffB); PG8_STAGE(PG8_SB(1, 1), b3 + hstep, voffB); PG8_STAGE(PG8_SA(1, 0), a3, voffA);
;             PG8_WAIT_V(8); PG8_WAIT_L(0); PG8_BAR; PG8_MMA(1, 0, At, B0); PG8_MMA(1, 1, At, B1); PG8_BAR; PG8_SCHED;
	s_setprio 0
	s_add_i32 s22, s63, s27
	s_mov_b32 m0, s22
	ds_read_b128 v[216:219], v160 offset:49152
	ds_read_b128 v[220:223], v160 offset:50176
	ds_read_b128 v[224:227], v160 offset:51200
	ds_read_b128 v[228:231], v160 offset:52224
	ds_read_b128 v[232:235], v160 offset:53248
	ds_read_b128 v[236:239], v160 offset:54272
	ds_read_b128 v[240:243], v160 offset:55296
	ds_read_b128 v[244:247], v160 offset:56320
	s_add_u32 vcc_lo, s20, 0x80
	s_addc_u32 vcc_hi, s21, 0
	global_load_lds_dwordx4 v2, vcc
	s_add_i32 m0, s22, 0x2000
	s_add_u32 s20, s20, 0x80080
	s_addc_u32 s21, s21, 0
	s_add_i32 s22, s64, s27
	s_add_u32 vcc_lo, s20, 0xfff80000
	s_addc_u32 vcc_hi, s21, -1
	global_load_lds_dwordx4 v0, vcc
	s_mov_b32 m0, s22
	s_nop 0
	global_load_lds_dwordx4 v2, s[20:21]
	s_add_i32 m0, s22, 0x2000
	s_nop 0
	global_load_lds_dwordx4 v0, s[20:21]
	v_lshl_add_u64 v[152:153], v[248:249], 0, s[36:37]
	s_mov_b32 m0, s34
	s_nop 0
	global_load_lds_dwordx4 v[152:153], off
	v_lshl_add_u64 v[152:153], v[250:251], 0, s[36:37]
	s_mov_b32 m0, s35
	s_nop 0
	global_load_lds_dwordx4 v[152:153], off
	s_waitcnt vmcnt(8)
	s_waitcnt lgkmcnt(0)
	s_setprio 1
	s_barrier
	v_mfma_f32_16x16x32_bf16 v[64:67], v[184:187], v[216:219], v[64:67]
	v_mfma_f32_16x16x32_bf16 v[60:63], v[192:195], v[216:219], v[60:63]
	v_mfma_f32_16x16x32_bf16 v[48:51], v[184:187], v[224:227], v[48:51]
	v_mfma_f32_16x16x32_bf16 v[44:47], v[192:195], v[224:227], v[44:47]
	v_mfma_f32_16x16x32_bf16 v[32:35], v[184:187], v[232:235], v[32:35]
	v_mfma_f32_16x16x32_bf16 v[28:31], v[192:195], v[232:235], v[28:31]
	v_mfma_f32_16x16x32_bf16 v[16:19], v[184:187], v[240:243], v[16:19]
	v_mfma_f32_16x16x32_bf16 v[12:15], v[192:195], v[240:243], v[12:15]
	v_mfma_f32_16x16x32_bf16 v[64:67], v[188:191], v[220:223], v[64:67]
	v_mfma_f32_16x16x32_bf16 v[60:63], v[196:199], v[220:223], v[60:63]
	v_mfma_f32_16x16x32_bf16 v[48:51], v[188:191], v[228:231], v[48:51]
	v_mfma_f32_16x16x32_bf16 v[44:47], v[196:199], v[228:231], v[44:47]
	v_mfma_f32_16x16x32_bf16 v[32:35], v[188:191], v[236:239], v[32:35]
	v_mfma_f32_16x16x32_bf16 v[28:31], v[196:199], v[236:239], v[28:31]
	v_mfma_f32_16x16x32_bf16 v[16:19], v[188:191], v[244:247], v[16:19]
	v_mfma_f32_16x16x32_bf16 v[12:15], v[196:199], v[244:247], v[12:15]
	v_mfma_f32_16x16x32_bf16 v[56:59], v[200:203], v[216:219], v[56:59]
	v_mfma_f32_16x16x32_bf16 v[52:55], v[208:211], v[216:219], v[52:55]
	v_mfma_f32_16x16x32_bf16 v[40:43], v[200:203], v[224:227], v[40:43]
	v_mfma_f32_16x16x32_bf16 v[36:39], v[208:211], v[224:227], v[36:39]
	v_mfma_f32_16x16x32_bf16 v[24:27], v[200:203], v[232:235], v[24:27]
	v_mfma_f32_16x16x32_bf16 v[20:23], v[208:211], v[232:235], v[20:23]
	v_mfma_f32_16x16x32_bf16 v[8:11], v[200:203], v[240:243], v[8:11]
	v_mfma_f32_16x16x32_bf16 v[4:7], v[208:211], v[240:243], v[4:7]
	v_mfma_f32_16x16x32_bf16 v[56:59], v[204:207], v[220:223], v[56:59]
	v_mfma_f32_16x16x32_bf16 v[52:55], v[212:215], v[220:223], v[52:55]
	v_mfma_f32_16x16x32_bf16 v[40:43], v[204:207], v[228:231], v[40:43]
	v_mfma_f32_16x16x32_bf16 v[36:39], v[212:215], v[228:231], v[36:39]
	v_mfma_f32_16x16x32_bf16 v[24:27], v[204:207], v[236:239], v[24:27]
	v_mfma_f32_16x16x32_bf16 v[20:23], v[212:215], v[236:239], v[20:23]
	v_mfma_f32_16x16x32_bf16 v[8:11], v[204:207], v[244:247], v[8:11]
	v_mfma_f32_16x16x32_bf16 v[4:7], v[212:215], v[244:247], v[4:7]
	s_barrier
	s_setprio 0
	s_add_i32 s57, s57, 2
	s_add_u32 s18, s18, 0x100
	s_addc_u32 s19, s19, 0
	s_add_u32 s51, s51, 0x100
	s_addc_u32 s56, s56, 0
	s_cmp_gt_u32 s57, 29

; #define PG8_STAGE(bufoff, gbase, voff) do { _Pragma("unroll") for (int _i = 0; _i < 2; ++_i) \
;         __builtin_amdgcn_global_load_lds((const unsigned*)((const char*)(gbase) + (voff)[_i]), (PG8_LAS unsigned*)(lds + (bufoff) + ldsw + _i * 8192), 16, 0, 0); } while (0)
; #define PG8_LDA(dst, b, h) do { _Pragma("unroll") for (int m = 0; m < 4; ++m) _Pragma("unroll") for (int k = 0; k < 2; ++k) dst[m][k] = *(const PG8_LAS bf16x8*)(lds + PG8_SA(b, h) + aoff + m * 2048 + k * 1024); } while (0)
; #define PG8_LDB(dst, b, h) do { _Pragma("unroll") for (int n = 0; n < 2; ++n) _Pragma("unroll") for (int k = 0; k < 2; ++k) dst[n][k] = *(const PG8_LAS bf16x8*)(lds + PG8_SB(b, h) + boff + n * 2048 + k * 1024); } while (0)
; #define PG8_MMA(ai, bj, At, Bt) do { __builtin_amdgcn_s_setprio(1); _Pragma("unroll") for (int m = 0; m < 4; ++m) _Pragma("unroll") for (int n = 0; n < 2; ++n) _Pragma("unroll") for (int k = 0; k < 2; ++k) \
;         acc[ai][bj][m][n] = __builtin_amdgcn_mfma_f32_16x16x32_bf16(Bt[n][k], At[m][k], acc[ai][bj][m][n], 0, 0, 0); __builtin_amdgcn_s_setprio(0); } while (0)
; #define PG8_WAIT_V(n) asm volatile("s_waitcnt vmcnt(" #n ")" ::: "memory")
; #define PG8_WAIT_L(n) asm volatile("s_waitcnt lgkmcnt(" #n ")" ::: "memory")
; #define PG8_BAR __builtin_amdgcn_s_barrier()
; #define PG8_SCHED __builtin_amdgcn_sched_barrier(0)
; template <class Epi, class Sched, bool ALIGN_EPI = false, bool SP2 = false>
; __device__ __forceinline__ void gemm_phase(PG8_LAS unsigned char* lds, const Gemm g, const Sched& S, const Epi& E) {
;     ...
;             PG8_LDB(B0, 0, 0); PG8_LDB(B1, 0, 1); PG8_SCHED; PG8_LDA(At, 0, 0); PG8_STAGE(PG8_SA(1, 1), a1 + hstep, voffA);
;             PG8_WAIT_V(8); PG8_WAIT_L(0); PG8_BAR; PG8_MMA(0, 0, At, B0); PG8_MMA(0, 1, At, B1); PG8_BAR; PG8_SCHED;
;             PG8_LDA(At, 0, 1); PG8_STAGE(PG8_SB(0, 0), b2, voffB); PG8_STAGE(PG8_SB(0, 1), b2 + hstep, voffB); PG8_STAGE(PG8_SA(0, 0), a2, voffA);
;             PG8_WAIT_V(8); PG8_WAIT_L(0); PG8_BAR; PG8_MMA(1, 0, At, B0); PG8_MMA(1, 1, At, B1); PG8_BAR; PG8_SCHED;
.LBB0_482:
	s_ashr_i32 s13, s12, 31
	s_lshl_b64 s[14:15], s[12:13], 20
	s_add_u32 s14, s54, s14
	s_addc_u32 s15, s55, s15
	s_and_b64 s[16:17], s[4:5], exec
	s_cselect_b32 s13, s15, s23
	s_cselect_b32 s19, s14, s22
	s_ashr_i32 s11, s10, 31
	s_lshl_b64 s[16:17], s[10:11], 20
	s_add_u32 s16, s29, s16
	s_addc_u32 s17, s30, s17
	s_and_b64 s[26:27], s[4:5], exec
	s_cselect_b32 s11, s17, s25
	s_cselect_b32 s56, s16, s24
	s_add_u32 s22, s22, 0x80080
	s_addc_u32 s23, s23, 0
	s_add_u32 s57, s24, 0x100
	s_addc_u32 s63, s25, 0
	s_mov_b32 s64, -2
	s_waitcnt lgkmcnt(0)
	s_add_u32 s24, s22, 0xfff80080
	s_addc_u32 s25, s23, -1
	s_add_i32 s65, 0, 0x10000
	s_cmp_eq_u32 s64, 28
	s_cselect_b32 s27, s13, s25
	s_cselect_b32 s26, s19, s24
	s_cselect_b32 s25, s11, s63
	s_cselect_b32 s24, s56, s57
	s_add_i32 s76, 0, 0x14000
	v_add_u32_e32 v162, s65, v185
	v_add_u32_e32 v166, s76, v185
	ds_read_b128 v[132:135], v162
	ds_read_b128 v[136:139], v162 offset:1024
	ds_read_b128 v[158:161], v162 offset:2048
	ds_read_b128 v[162:165], v162 offset:3072
	ds_read_b128 v[188:191], v166
	ds_read_b128 v[192:195], v166 offset:1024
	ds_read_b128 v[196:199], v166 offset:2048
	ds_read_b128 v[200:203], v166 offset:3072
	s_add_i32 m0, s21, 0xc000
	ds_read_b128 v[204:207], v187
	ds_read_b128 v[208:211], v187 offset:1024
	ds_read_b128 v[212:215], v187 offset:2048
	ds_read_b128 v[216:219], v187 offset:3072
	ds_read_b128 v[220:223], v187 offset:4096
	ds_read_b128 v[224:227], v187 offset:5120
	ds_read_b128 v[228:231], v187 offset:6144
	ds_read_b128 v[232:235], v187 offset:7168
	global_load_lds_dwordx4 v154, s[22:23]
	s_add_i32 m0, s21, 0xe000
	s_nop 0
	global_load_lds_dwordx4 v156, s[22:23]
	s_waitcnt vmcnt(24)
	s_waitcnt lgkmcnt(0)
	s_setprio 1
	s_barrier
	v_mfma_f32_16x16x32_bf16 v[128:131], v[132:135], v[204:207], 0
	v_mfma_f32_16x16x32_bf16 v[124:127], v[158:161], v[204:207], 0
	v_mfma_f32_16x16x32_bf16 v[112:115], v[132:135], v[212:215], 0
	v_mfma_f32_16x16x32_bf16 v[108:111], v[158:161], v[212:215], 0
	v_mfma_f32_16x16x32_bf16 v[96:99], v[132:135], v[220:223], 0
	v_mfma_f32_16x16x32_bf16 v[92:95], v[158:161], v[220:223], 0
	v_mfma_f32_16x16x32_bf16 v[80:83], v[132:135], v[228:231], 0
	v_mfma_f32_16x16x32_bf16 v[76:79], v[158:161], v[228:231], 0
	v_mfma_f32_16x16x32_bf16 v[128:131], v[136:139], v[208:211], v[128:131]
	v_mfma_f32_16x16x32_bf16 v[124:127], v[162:165], v[208:211], v[124:127]
	v_mfma_f32_16x16x32_bf16 v[112:115], v[136:139], v[216:219], v[112:115]
	v_mfma_f32_16x16x32_bf16 v[108:111], v[162:165], v[216:219], v[108:111]
	v_mfma_f32_16x16x32_bf16 v[96:99], v[136:139], v[224:227], v[96:99]
	v_mfma_f32_16x16x32_bf16 v[92:95], v[162:165], v[224:227], v[92:95]
	v_mfma_f32_16x16x32_bf16 v[80:83], v[136:139], v[232:235], v[80:83]
	v_mfma_f32_16x16x32_bf16 v[76:79], v[162:165], v[232:235], v[76:79]
	v_mfma_f32_16x16x32_bf16 v[120:123], v[188:191], v[204:207], 0
	v_mfma_f32_16x16x32_bf16 v[116:119], v[196:199], v[204:207], 0
	v_mfma_f32_16x16x32_bf16 v[104:107], v[188:191], v[212:215], 0
	v_mfma_f32_16x16x32_bf16 v[100:103], v[196:199], v[212:215], 0
	v_mfma_f32_16x16x32_bf16 v[88:91], v[188:191], v[220:223], 0
	v_mfma_f32_16x16x32_bf16 v[84:87], v[196:199], v[220:223], 0
	v_mfma_f32_16x16x32_bf16 v[72:75], v[188:191], v[228:231], 0
	v_mfma_f32_16x16x32_bf16 v[68:71], v[196:199], v[228:231], 0
	v_mfma_f32_16x16x32_bf16 v[120:123], v[192:195], v[208:211], v[120:123]
	v_mfma_f32_16x16x32_bf16 v[116:119], v[200:203], v[208:211], v[116:119]
	v_mfma_f32_16x16x32_bf16 v[104:107], v[192:195], v[216:219], v[104:107]
	v_mfma_f32_16x16x32_bf16 v[100:103], v[200:203], v[216:219], v[100:103]
	v_mfma_f32_16x16x32_bf16 v[88:91], v[192:195], v[224:227], v[88:91]
	v_mfma_f32_16x16x32_bf16 v[84:87], v[200:203], v[224:227], v[84:87]
	v_mfma_f32_16x16x32_bf16 v[72:75], v[192:195], v[232:235], v[72:75]
	v_mfma_f32_16x16x32_bf16 v[68:71], v[200:203], v[232:235], v[68:71]
	s_barrier
	s_setprio 0
	s_add_i32 s65, s65, s31
	s_mov_b32 m0, s65
	ds_read_b128 v[204:207], v187 offset:16384
	ds_read_b128 v[208:211], v187 offset:17408
	ds_read_b128 v[212:215], v187 offset:18432
	ds_read_b128 v[216:219], v187 offset:19456
	ds_read_b128 v[220:223], v187 offset:20480
	ds_read_b128 v[224:227], v187 offset:21504
	ds_read_b128 v[228:231], v187 offset:22528
	ds_read_b128 v[232:235], v187 offset:23552
	global_load_lds_dwordx4 v2, s[24:25]
	s_add_i32 m0, s65, 0x2000
	s_add_u32 s66, s24, 0x80000
	s_addc_u32 s67, s25, 0
	s_add_i32 s65, s76, s31
	global_load_lds_dwordx4 v152, s[24:25]
	s_mov_b32 m0, s65
	v_lshl_add_u64 v[240:241], s[26:27], 0, v[150:151]
	global_load_lds_dwordx4 v2, s[66:67]
	s_add_i32 m0, s65, 0x2000
	s_nop 0
	global_load_lds_dwordx4 v152, s[66:67]
	v_lshl_add_u64 v[238:239], s[26:27], 0, v[0:1]
	s_mov_b32 m0, s21
	s_nop 0
	global_load_lds_dwordx4 v[238:239], off
	s_mov_b32 m0, s34
	s_nop 0
	global_load_lds_dwordx4 v[240:241], off
	s_waitcnt vmcnt(8)
	s_waitcnt lgkmcnt(0)
	s_setprio 1
	s_barrier
; #define PG8_STAGE(bufoff, gbase, voff) do { _Pragma("unroll") for (int _i = 0; _i < 2; ++_i) \
;         __builtin_amdgcn_global_load_lds((const unsigned*)((const char*)(gbase) + (voff)[_i]), (PG8_LAS unsigned*)(lds + (bufoff) + ldsw + _i * 8192), 16, 0, 0); } while (0)
; #define PG8_LDA(dst, b, h) do { _Pragma("unroll") for (int m = 0; m < 4; ++m) _Pragma("unroll") for (int k = 0; k < 2; ++k) dst[m][k] = *(const PG8_LAS bf16x8*)(lds + PG8_SA(b, h) + aoff + m * 2048 + k * 1024); } while (0)
; #define PG8_LDB(dst, b, h) do { _Pragma("unroll") for (int n = 0; n < 2; ++n) _Pragma("unroll") for (int k = 0; k < 2; ++k) dst[n][k] = *(const PG8_LAS bf16x8*)(lds + PG8_SB(b, h) + boff + n * 2048 + k * 1024); } while (0)
; #define PG8_MMA(ai, bj, At, Bt) do { __builtin_amdgcn_s_setprio(1); _Pragma("unroll") for (int m = 0; m < 4; ++m) _Pragma("unroll") for (int n = 0; n < 2; ++n) _Pragma("unroll") for (int k = 0; k < 2; ++k) \
;         acc[ai][bj][m][n] = __builtin_amdgcn_mfma_f32_16x16x32_bf16(Bt[n][k], At[m][k], acc[ai][bj][m][n], 0, 0, 0); __builtin_amdgcn_s_setprio(0); } while (0)
; #define PG8_WAIT_V(n) asm volatile("s_waitcnt vmcnt(" #n ")" ::: "memory")
; #define PG8_WAIT_L(n) asm volatile("s_waitcnt lgkmcnt(" #n ")" ::: "memory")
; #define PG8_BAR __builtin_amdgcn_s_barrier()
; #define PG8_SCHED __builtin_amdgcn_sched_barrier(0)
; template <class Epi, class Sched, bool ALIGN_EPI = false, bool SP2 = false>
; __device__ __forceinline__ void gemm_phase(PG8_LAS unsigned char* lds, const Gemm g, const Sched& S, const Epi& E) {
;     ...
;             PG8_WAIT_V(8); PG8_WAIT_L(0); PG8_BAR; PG8_MMA(1, 0, At, B0); PG8_MMA(1, 1, At, B1); PG8_BAR; PG8_SCHED;
;             PG8_LDB(B0, 1, 0); PG8_LDB(B1, 1, 1); PG8_SCHED; PG8_LDA(At, 1, 0); PG8_STAGE(PG8_SA(0, 1), a2 + hstep, voffA);
;             PG8_WAIT_V(8); PG8_WAIT_L(0); PG8_BAR; PG8_MMA(0, 0, At, B0); PG8_MMA(0, 1, At, B1); PG8_BAR; PG8_SCHED;
	v_mfma_f32_16x16x32_bf16 v[64:67], v[132:135], v[204:207], 0
	v_mfma_f32_16x16x32_bf16 v[60:63], v[158:161], v[204:207], 0
	v_mfma_f32_16x16x32_bf16 v[48:51], v[132:135], v[212:215], 0
	v_mfma_f32_16x16x32_bf16 v[44:47], v[158:161], v[212:215], 0
	v_mfma_f32_16x16x32_bf16 v[32:35], v[132:135], v[220:223], 0
	v_mfma_f32_16x16x32_bf16 v[28:31], v[158:161], v[220:223], 0
	v_mfma_f32_16x16x32_bf16 v[16:19], v[132:135], v[228:231], 0
	v_mfma_f32_16x16x32_bf16 v[12:15], v[158:161], v[228:231], 0
	v_mfma_f32_16x16x32_bf16 v[64:67], v[136:139], v[208:211], v[64:67]
	v_mfma_f32_16x16x32_bf16 v[60:63], v[162:165], v[208:211], v[60:63]
	v_mfma_f32_16x16x32_bf16 v[48:51], v[136:139], v[216:219], v[48:51]
	v_mfma_f32_16x16x32_bf16 v[44:47], v[162:165], v[216:219], v[44:47]
	v_mfma_f32_16x16x32_bf16 v[32:35], v[136:139], v[224:227], v[32:35]
	v_mfma_f32_16x16x32_bf16 v[28:31], v[162:165], v[224:227], v[28:31]
	v_mfma_f32_16x16x32_bf16 v[16:19], v[136:139], v[232:235], v[16:19]
	v_mfma_f32_16x16x32_bf16 v[12:15], v[162:165], v[232:235], v[12:15]
	v_mfma_f32_16x16x32_bf16 v[56:59], v[188:191], v[204:207], 0
	v_mfma_f32_16x16x32_bf16 v[52:55], v[196:199], v[204:207], 0
	v_mfma_f32_16x16x32_bf16 v[40:43], v[188:191], v[212:215], 0
	v_mfma_f32_16x16x32_bf16 v[36:39], v[196:199], v[212:215], 0
	v_mfma_f32_16x16x32_bf16 v[24:27], v[188:191], v[220:223], 0
	v_mfma_f32_16x16x32_bf16 v[20:23], v[196:199], v[220:223], 0
	v_mfma_f32_16x16x32_bf16 v[8:11], v[188:191], v[228:231], 0
	v_mfma_f32_16x16x32_bf16 v[4:7], v[196:199], v[228:231], 0
	v_mfma_f32_16x16x32_bf16 v[56:59], v[192:195], v[208:211], v[56:59]
	v_mfma_f32_16x16x32_bf16 v[52:55], v[200:203], v[208:211], v[52:55]
	v_mfma_f32_16x16x32_bf16 v[40:43], v[192:195], v[216:219], v[40:43]
	v_mfma_f32_16x16x32_bf16 v[36:39], v[200:203], v[216:219], v[36:39]
	v_mfma_f32_16x16x32_bf16 v[24:27], v[192:195], v[224:227], v[24:27]
	v_mfma_f32_16x16x32_bf16 v[20:23], v[200:203], v[224:227], v[20:23]
	v_mfma_f32_16x16x32_bf16 v[8:11], v[192:195], v[232:235], v[8:11]
	v_mfma_f32_16x16x32_bf16 v[4:7], v[200:203], v[232:235], v[4:7]
	s_barrier
	s_setprio 0
	s_add_i32 s65, 0, 0x18000
	s_add_i32 s66, 0, 0x1c000
	v_add_u32_e32 v162, s65, v185
	v_add_u32_e32 v200, s66, v185
	ds_read_b128 v[132:135], v162
	ds_read_b128 v[136:139], v162 offset:1024
	ds_read_b128 v[158:161], v162 offset:2048
	ds_read_b128 v[162:165], v162 offset:3072
	ds_read_b128 v[188:191], v200
	ds_read_b128 v[192:195], v200 offset:1024
	ds_read_b128 v[196:199], v200 offset:2048
	ds_read_b128 v[200:203], v200 offset:3072
	s_add_u32 s26, s26, 0x80000
	s_addc_u32 s27, s27, 0
	s_mov_b32 m0, s35
	ds_read_b128 v[204:207], v187 offset:32768
	ds_read_b128 v[208:211], v187 offset:33792
	ds_read_b128 v[212:215], v187 offset:34816
	ds_read_b128 v[216:219], v187 offset:35840
	ds_read_b128 v[220:223], v187 offset:36864
	ds_read_b128 v[224:227], v187 offset:37888
	ds_read_b128 v[228:231], v187 offset:38912
	ds_read_b128 v[232:235], v187 offset:39936
	global_load_lds_dwordx4 v0, s[26:27]
	s_mov_b32 m0, s42
	s_nop 0
	global_load_lds_dwordx4 v150, s[26:27]
	s_waitcnt vmcnt(8)
	s_waitcnt lgkmcnt(0)
	s_setprio 1
	s_barrier
	v_mfma_f32_16x16x32_bf16 v[128:131], v[132:135], v[204:207], v[128:131]
	v_mfma_f32_16x16x32_bf16 v[124:127], v[158:161], v[204:207], v[124:127]
	v_mfma_f32_16x16x32_bf16 v[112:115], v[132:135], v[212:215], v[112:115]
	v_mfma_f32_16x16x32_bf16 v[108:111], v[158:161], v[212:215], v[108:111]
	v_mfma_f32_16x16x32_bf16 v[96:99], v[132:135], v[220:223], v[96:99]
	v_mfma_f32_16x16x32_bf16 v[92:95], v[158:161], v[220:223], v[92:95]
	v_mfma_f32_16x16x32_bf16 v[80:83], v[132:135], v[228:231], v[80:83]
	v_mfma_f32_16x16x32_bf16 v[76:79], v[158:161], v[228:231], v[76:79]
	v_mfma_f32_16x16x32_bf16 v[128:131], v[136:139], v[208:211], v[128:131]
	v_mfma_f32_16x16x32_bf16 v[124:127], v[162:165], v[208:211], v[124:127]
	v_mfma_f32_16x16x32_bf16 v[112:115], v[136:139], v[216:219], v[112:115]
	v_mfma_f32_16x16x32_bf16 v[108:111], v[162:165], v[216:219], v[108:111]
	v_mfma_f32_16x16x32_bf16 v[96:99], v[136:139], v[224:227], v[96:99]
	v_mfma_f32_16x16x32_bf16 v[92:95], v[162:165], v[224:227], v[92:95]
	v_mfma_f32_16x16x32_bf16 v[80:83], v[136:139], v[232:235], v[80:83]
	v_mfma_f32_16x16x32_bf16 v[76:79], v[162:165], v[232:235], v[76:79]
	v_mfma_f32_16x16x32_bf16 v[120:123], v[188:191], v[204:207], v[120:123]
	v_mfma_f32_16x16x32_bf16 v[116:119], v[196:199], v[204:207], v[116:119]
	v_mfma_f32_16x16x32_bf16 v[104:107], v[188:191], v[212:215], v[104:107]
	v_mfma_f32_16x16x32_bf16 v[100:103], v[196:199], v[212:215], v[100:103]
	v_mfma_f32_16x16x32_bf16 v[88:91], v[188:191], v[220:223], v[88:91]
	v_mfma_f32_16x16x32_bf16 v[84:87], v[196:199], v[220:223], v[84:87]
	v_mfma_f32_16x16x32_bf16 v[72:75], v[188:191], v[228:231], v[72:75]
	v_mfma_f32_16x16x32_bf16 v[68:71], v[196:199], v[228:231], v[68:71]
	v_mfma_f32_16x16x32_bf16 v[120:123], v[192:195], v[208:211], v[120:123]
	v_mfma_f32_16x16x32_bf16 v[116:119], v[200:203], v[208:211], v[116:119]
	v_mfma_f32_16x16x32_bf16 v[104:107], v[192:195], v[216:219], v[104:107]
	v_mfma_f32_16x16x32_bf16 v[100:103], v[200:203], v[216:219], v[100:103]
	v_mfma_f32_16x16x32_bf16 v[88:91], v[192:195], v[224:227], v[88:91]
	v_mfma_f32_16x16x32_bf16 v[84:87], v[200:203], v[224:227], v[84:87]
	v_mfma_f32_16x16x32_bf16 v[72:75], v[192:195], v[232:235], v[72:75]
	v_mfma_f32_16x16x32_bf16 v[68:71], v[200:203], v[232:235], v[68:71]
	s_barrier
; #define PG8_STAGE(bufoff, gbase, voff) do { _Pragma("unroll") for (int _i = 0; _i < 2; ++_i) \
;         __builtin_amdgcn_global_load_lds((const unsigned*)((const char*)(gbase) + (voff)[_i]), (PG8_LAS unsigned*)(lds + (bufoff) + ldsw + _i * 8192), 16, 0, 0); } while (0)
; #define PG8_LDA(dst, b, h) do { _Pragma("unroll") for (int m = 0; m < 4; ++m) _Pragma("unroll") for (int k = 0; k < 2; ++k) dst[m][k] = *(const PG8_LAS bf16x8*)(lds + PG8_SA(b, h) + aoff + m * 2048 + k * 1024); } while (0)
; #define PG8_MMA(ai, bj, At, Bt) do { __builtin_amdgcn_s_setprio(1); _Pragma("unroll") for (int m = 0; m < 4; ++m) _Pragma("unroll") for (int n = 0; n < 2; ++n) _Pragma("unroll") for (int k = 0; k < 2; ++k) \
;         acc[ai][bj][m][n] = __builtin_amdgcn_mfma_f32_16x16x32_bf16(Bt[n][k], At[m][k], acc[ai][bj][m][n], 0, 0, 0); __builtin_amdgcn_s_setprio(0); } while (0)
; #define PG8_WAIT_V(n) asm volatile("s_waitcnt vmcnt(" #n ")" ::: "memory")
; #define PG8_WAIT_L(n) asm volatile("s_waitcnt lgkmcnt(" #n ")" ::: "memory")
; #define PG8_BAR __builtin_amdgcn_s_barrier()
; #define PG8_SCHED __builtin_amdgcn_sched_barrier(0)
; template <class Epi, class Sched, bool ALIGN_EPI = false, bool SP2 = false>
; __device__ __forceinline__ void gemm_phase(PG8_LAS unsigned char* lds, const Gemm g, const Sched& S, const Epi& E) {
;     ...
;             PG8_LDA(At, 1, 1); PG8_STAGE(PG8_SB(1, 0), b3, voffB); PG8_STAGE(PG8_SB(1, 1), b3 + hstep, voffB); PG8_STAGE(PG8_SA(1, 0), a3, voffA);
;             PG8_WAIT_V(8); PG8_WAIT_L(0); PG8_BAR; PG8_MMA(1, 0, At, B0); PG8_MMA(1, 1, At, B1); PG8_BAR; PG8_SCHED;
	s_setprio 0
	s_add_i32 s26, s65, s31
	s_mov_b32 m0, s26
	ds_read_b128 v[204:207], v187 offset:49152
	ds_read_b128 v[208:211], v187 offset:50176
	ds_read_b128 v[212:215], v187 offset:51200
	ds_read_b128 v[216:219], v187 offset:52224
	ds_read_b128 v[220:223], v187 offset:53248
	ds_read_b128 v[224:227], v187 offset:54272
	ds_read_b128 v[228:231], v187 offset:55296
	ds_read_b128 v[232:235], v187 offset:56320
	s_add_u32 vcc_lo, s24, 0x80
	s_addc_u32 vcc_hi, s25, 0
	global_load_lds_dwordx4 v2, vcc
	s_add_i32 m0, s26, 0x2000
	s_add_u32 s24, s24, 0x80080
	s_addc_u32 s25, s25, 0
	s_add_i32 s26, s66, s31
	s_add_u32 vcc_lo, s24, 0xfff80000
	s_addc_u32 vcc_hi, s25, -1
	global_load_lds_dwordx4 v152, vcc
	s_mov_b32 m0, s26
	s_nop 0
	global_load_lds_dwordx4 v2, s[24:25]
	s_add_i32 m0, s26, 0x2000
	s_nop 0
	global_load_lds_dwordx4 v152, s[24:25]
	v_lshl_add_u64 v[166:167], v[238:239], 0, s[36:37]
	s_mov_b32 m0, s44
	s_nop 0
	global_load_lds_dwordx4 v[166:167], off
	v_lshl_add_u64 v[166:167], v[240:241], 0, s[36:37]
	s_mov_b32 m0, s45
	s_nop 0
	global_load_lds_dwordx4 v[166:167], off
	s_waitcnt vmcnt(8)
	s_waitcnt lgkmcnt(0)
	s_setprio 1
	s_barrier
	v_mfma_f32_16x16x32_bf16 v[64:67], v[132:135], v[204:207], v[64:67]
	v_mfma_f32_16x16x32_bf16 v[60:63], v[158:161], v[204:207], v[60:63]
	v_mfma_f32_16x16x32_bf16 v[48:51], v[132:135], v[212:215], v[48:51]
	v_mfma_f32_16x16x32_bf16 v[44:47], v[158:161], v[212:215], v[44:47]
	v_mfma_f32_16x16x32_bf16 v[32:35], v[132:135], v[220:223], v[32:35]
	v_mfma_f32_16x16x32_bf16 v[28:31], v[158:161], v[220:223], v[28:31]
	v_mfma_f32_16x16x32_bf16 v[16:19], v[132:135], v[228:231], v[16:19]
	v_mfma_f32_16x16x32_bf16 v[12:15], v[158:161], v[228:231], v[12:15]
	v_mfma_f32_16x16x32_bf16 v[64:67], v[136:139], v[208:211], v[64:67]
	v_mfma_f32_16x16x32_bf16 v[60:63], v[162:165], v[208:211], v[60:63]
	v_mfma_f32_16x16x32_bf16 v[48:51], v[136:139], v[216:219], v[48:51]
	v_mfma_f32_16x16x32_bf16 v[44:47], v[162:165], v[216:219], v[44:47]
	v_mfma_f32_16x16x32_bf16 v[32:35], v[136:139], v[224:227], v[32:35]
	v_mfma_f32_16x16x32_bf16 v[28:31], v[162:165], v[224:227], v[28:31]
	v_mfma_f32_16x16x32_bf16 v[16:19], v[136:139], v[232:235], v[16:19]
	v_mfma_f32_16x16x32_bf16 v[12:15], v[162:165], v[232:235], v[12:15]
	v_mfma_f32_16x16x32_bf16 v[56:59], v[188:191], v[204:207], v[56:59]
	v_mfma_f32_16x16x32_bf16 v[52:55], v[196:199], v[204:207], v[52:55]
	v_mfma_f32_16x16x32_bf16 v[40:43], v[188:191], v[212:215], v[40:43]
	v_mfma_f32_16x16x32_bf16 v[36:39], v[196:199], v[212:215], v[36:39]
	v_mfma_f32_16x16x32_bf16 v[24:27], v[188:191], v[220:223], v[24:27]
	v_mfma_f32_16x16x32_bf16 v[20:23], v[196:199], v[220:223], v[20:23]
	v_mfma_f32_16x16x32_bf16 v[8:11], v[188:191], v[228:231], v[8:11]
	v_mfma_f32_16x16x32_bf16 v[4:7], v[196:199], v[228:231], v[4:7]
	v_mfma_f32_16x16x32_bf16 v[56:59], v[192:195], v[208:211], v[56:59]
	v_mfma_f32_16x16x32_bf16 v[52:55], v[200:203], v[208:211], v[52:55]
	v_mfma_f32_16x16x32_bf16 v[40:43], v[192:195], v[216:219], v[40:43]
	v_mfma_f32_16x16x32_bf16 v[36:39], v[200:203], v[216:219], v[36:39]
	v_mfma_f32_16x16x32_bf16 v[24:27], v[192:195], v[224:227], v[24:27]
	v_mfma_f32_16x16x32_bf16 v[20:23], v[200:203], v[224:227], v[20:23]
	v_mfma_f32_16x16x32_bf16 v[8:11], v[192:195], v[232:235], v[8:11]
	v_mfma_f32_16x16x32_bf16 v[4:7], v[200:203], v[232:235], v[4:7]
	s_barrier
	s_setprio 0
	s_add_i32 s64, s64, 2
	s_add_u32 s22, s22, 0x100
	s_addc_u32 s23, s23, 0
	s_add_u32 s57, s57, 0x100
	s_addc_u32 s63, s63, 0
	s_cmp_gt_u32 s64, 29

; #define PG8_STAGE(bufoff, gbase, voff) do { _Pragma("unroll") for (int _i = 0; _i < 2; ++_i) \
;         __builtin_amdgcn_global_load_lds((const unsigned*)((const char*)(gbase) + (voff)[_i]), (PG8_LAS unsigned*)(lds + (bufoff) + ldsw + _i * 8192), 16, 0, 0); } while (0)
; #define PG8_LDA(dst, b, h) do { _Pragma("unroll") for (int m = 0; m < 4; ++m) _Pragma("unroll") for (int k = 0; k < 2; ++k) dst[m][k] = *(const PG8_LAS bf16x8*)(lds + PG8_SA(b, h) + aoff + m * 2048 + k * 1024); } while (0)
; #define PG8_LDB(dst, b, h) do { _Pragma("unroll") for (int n = 0; n < 2; ++n) _Pragma("unroll") for (int k = 0; k < 2; ++k) dst[n][k] = *(const PG8_LAS bf16x8*)(lds + PG8_SB(b, h) + boff + n * 2048 + k * 1024); } while (0)
; #define PG8_MMA(ai, bj, At, Bt) do { __builtin_amdgcn_s_setprio(1); _Pragma("unroll") for (int m = 0; m < 4; ++m) _Pragma("unroll") for (int n = 0; n < 2; ++n) _Pragma("unroll") for (int k = 0; k < 2; ++k) \
;         acc[ai][bj][m][n] = __builtin_amdgcn_mfma_f32_16x16x32_bf16(Bt[n][k], At[m][k], acc[ai][bj][m][n], 0, 0, 0); __builtin_amdgcn_s_setprio(0); } while (0)
; #define PG8_WAIT_V(n) asm volatile("s_waitcnt vmcnt(" #n ")" ::: "memory")
; #define PG8_WAIT_L(n) asm volatile("s_waitcnt lgkmcnt(" #n ")" ::: "memory")
; #define PG8_BAR __builtin_amdgcn_s_barrier()
; #define PG8_SCHED __builtin_amdgcn_sched_barrier(0)
; template <class Epi, class Sched, bool ALIGN_EPI = false, bool SP2 = false>
; __device__ __forceinline__ void gemm_phase(PG8_LAS unsigned char* lds, const Gemm g, const Sched& S, const Epi& E) {
;     ...
;             PG8_LDB(B0, 0, 0); PG8_LDB(B1, 0, 1); PG8_SCHED; PG8_LDA(At, 0, 0); PG8_STAGE(PG8_SA(1, 1), a1 + hstep, voffA);
;             PG8_WAIT_V(8); PG8_WAIT_L(0); PG8_BAR; PG8_MMA(0, 0, At, B0); PG8_MMA(0, 1, At, B1); PG8_BAR; PG8_SCHED;
;             PG8_LDA(At, 0, 1); PG8_STAGE(PG8_SB(0, 0), b2, voffB); PG8_STAGE(PG8_SB(0, 1), b2 + hstep, voffB); PG8_STAGE(PG8_SA(0, 0), a2, voffA);
;             PG8_WAIT_V(8); PG8_WAIT_L(0); PG8_BAR; PG8_MMA(1, 0, At, B0); PG8_MMA(1, 1, At, B1); PG8_BAR; PG8_SCHED;
.LBB0_566:
	s_ashr_i32 s11, s10, 31
	s_lshl_b64 s[12:13], s[10:11], 20
	s_add_u32 s12, s46, s12
	s_addc_u32 s13, s47, s13
	s_and_b64 s[14:15], s[2:3], exec
	s_cselect_b32 s11, s13, s19
	s_cselect_b32 s45, s12, s18
	s_ashr_i32 s9, s8, 31
	s_lshl_b64 s[14:15], s[8:9], 20
	s_add_u32 s14, s25, s14
	s_addc_u32 s15, s26, s15
	s_and_b64 s[22:23], s[2:3], exec
	s_cselect_b32 s9, s15, s21
	s_cselect_b32 s50, s14, s20
	s_add_u32 s18, s18, 0x80080
	s_addc_u32 s19, s19, 0
	s_add_u32 s51, s20, 0x100
	s_addc_u32 s56, s21, 0
	s_mov_b32 s57, -2
	s_add_u32 s20, s18, 0xfff80080
	s_addc_u32 s21, s19, -1
	s_add_i32 s63, 0, 0x10000
	s_cmp_eq_u32 s57, 28
	s_cselect_b32 s23, s11, s21
	s_cselect_b32 s22, s45, s20
	v_add_u32_e32 v150, s63, v153
	s_cselect_b32 s21, s9, s56
	s_cselect_b32 s20, s50, s51
	s_add_i32 s66, 0, 0x14000
	ds_read_b128 v[184:187], v150
	ds_read_b128 v[188:191], v150 offset:1024
	ds_read_b128 v[192:195], v150 offset:2048
	ds_read_b128 v[196:199], v150 offset:3072
	v_add_u32_e32 v150, s66, v153
	ds_read_b128 v[200:203], v150
	ds_read_b128 v[204:207], v150 offset:1024
	ds_read_b128 v[208:211], v150 offset:2048
	ds_read_b128 v[212:215], v150 offset:3072
	s_add_i32 m0, s29, 0xc000
	ds_read_b128 v[216:219], v155
	ds_read_b128 v[220:223], v155 offset:1024
	ds_read_b128 v[224:227], v155 offset:2048
	ds_read_b128 v[228:231], v155 offset:3072
	ds_read_b128 v[232:235], v155 offset:4096
	ds_read_b128 v[236:239], v155 offset:5120
	ds_read_b128 v[240:243], v155 offset:6144
	ds_read_b128 v[244:247], v155 offset:7168
	global_load_lds_dwordx4 v136, s[18:19]
	s_add_i32 m0, s29, 0xe000
	s_nop 0
	global_load_lds_dwordx4 v138, s[18:19]
	s_waitcnt vmcnt(24)
	s_waitcnt lgkmcnt(0)
	s_setprio 1
	s_barrier
	v_mfma_f32_16x16x32_bf16 v[128:131], v[184:187], v[216:219], 0
	v_mfma_f32_16x16x32_bf16 v[120:123], v[192:195], v[216:219], 0
	v_mfma_f32_16x16x32_bf16 v[112:115], v[184:187], v[224:227], 0
	v_mfma_f32_16x16x32_bf16 v[104:107], v[192:195], v[224:227], 0
	v_mfma_f32_16x16x32_bf16 v[96:99], v[184:187], v[232:235], 0
	v_mfma_f32_16x16x32_bf16 v[88:91], v[192:195], v[232:235], 0
	v_mfma_f32_16x16x32_bf16 v[80:83], v[184:187], v[240:243], 0
	v_mfma_f32_16x16x32_bf16 v[72:75], v[192:195], v[240:243], 0
	v_mfma_f32_16x16x32_bf16 v[128:131], v[188:191], v[220:223], v[128:131]
	v_mfma_f32_16x16x32_bf16 v[120:123], v[196:199], v[220:223], v[120:123]
	v_mfma_f32_16x16x32_bf16 v[112:115], v[188:191], v[228:231], v[112:115]
	v_mfma_f32_16x16x32_bf16 v[104:107], v[196:199], v[228:231], v[104:107]
	v_mfma_f32_16x16x32_bf16 v[96:99], v[188:191], v[236:239], v[96:99]
	v_mfma_f32_16x16x32_bf16 v[88:91], v[196:199], v[236:239], v[88:91]
	v_mfma_f32_16x16x32_bf16 v[80:83], v[188:191], v[244:247], v[80:83]
	v_mfma_f32_16x16x32_bf16 v[72:75], v[196:199], v[244:247], v[72:75]
	v_mfma_f32_16x16x32_bf16 v[124:127], v[200:203], v[216:219], 0
	v_mfma_f32_16x16x32_bf16 v[116:119], v[208:211], v[216:219], 0
	v_mfma_f32_16x16x32_bf16 v[108:111], v[200:203], v[224:227], 0
	v_mfma_f32_16x16x32_bf16 v[100:103], v[208:211], v[224:227], 0
	v_mfma_f32_16x16x32_bf16 v[92:95], v[200:203], v[232:235], 0
	v_mfma_f32_16x16x32_bf16 v[84:87], v[208:211], v[232:235], 0
	v_mfma_f32_16x16x32_bf16 v[76:79], v[200:203], v[240:243], 0
	v_mfma_f32_16x16x32_bf16 v[68:71], v[208:211], v[240:243], 0
	v_mfma_f32_16x16x32_bf16 v[124:127], v[204:207], v[220:223], v[124:127]
	v_mfma_f32_16x16x32_bf16 v[116:119], v[212:215], v[220:223], v[116:119]
	v_mfma_f32_16x16x32_bf16 v[108:111], v[204:207], v[228:231], v[108:111]
	v_mfma_f32_16x16x32_bf16 v[100:103], v[212:215], v[228:231], v[100:103]
	v_mfma_f32_16x16x32_bf16 v[92:95], v[204:207], v[236:239], v[92:95]
	v_mfma_f32_16x16x32_bf16 v[84:87], v[212:215], v[236:239], v[84:87]
	v_mfma_f32_16x16x32_bf16 v[76:79], v[204:207], v[244:247], v[76:79]
	v_mfma_f32_16x16x32_bf16 v[68:71], v[212:215], v[244:247], v[68:71]
	s_barrier
	s_setprio 0
	s_add_i32 s63, s63, s27
	s_mov_b32 m0, s63
	ds_read_b128 v[216:219], v155 offset:16384
	ds_read_b128 v[220:223], v155 offset:17408
	ds_read_b128 v[224:227], v155 offset:18432
	ds_read_b128 v[228:231], v155 offset:19456
	ds_read_b128 v[232:235], v155 offset:20480
	ds_read_b128 v[236:239], v155 offset:21504
	ds_read_b128 v[240:243], v155 offset:22528
	ds_read_b128 v[244:247], v155 offset:23552
	global_load_lds_dwordx4 v2, s[20:21]
	s_add_i32 m0, s63, 0x2000
	s_add_u32 s64, s20, 0x80000
	s_addc_u32 s65, s21, 0
	s_add_i32 s63, s66, s27
	global_load_lds_dwordx4 v0, s[20:21]
	s_mov_b32 m0, s63
	v_lshl_add_u64 v[250:251], s[22:23], 0, v[132:133]
	global_load_lds_dwordx4 v2, s[64:65]
	s_add_i32 m0, s63, 0x2000
	s_nop 0
	global_load_lds_dwordx4 v0, s[64:65]
	v_lshl_add_u64 v[248:249], s[22:23], 0, v[134:135]
	s_mov_b32 m0, s29
	s_nop 0
	global_load_lds_dwordx4 v[248:249], off
	s_mov_b32 m0, s30
	s_nop 0
	global_load_lds_dwordx4 v[250:251], off
	s_waitcnt vmcnt(8)
	s_waitcnt lgkmcnt(0)
	s_setprio 1
	s_barrier
; #define PG8_STAGE(bufoff, gbase, voff) do { _Pragma("unroll") for (int _i = 0; _i < 2; ++_i) \
;         __builtin_amdgcn_global_load_lds((const unsigned*)((const char*)(gbase) + (voff)[_i]), (PG8_LAS unsigned*)(lds + (bufoff) + ldsw + _i * 8192), 16, 0, 0); } while (0)
; #define PG8_LDA(dst, b, h) do { _Pragma("unroll") for (int m = 0; m < 4; ++m) _Pragma("unroll") for (int k = 0; k < 2; ++k) dst[m][k] = *(const PG8_LAS bf16x8*)(lds + PG8_SA(b, h) + aoff + m * 2048 + k * 1024); } while (0)
; #define PG8_LDB(dst, b, h) do { _Pragma("unroll") for (int n = 0; n < 2; ++n) _Pragma("unroll") for (int k = 0; k < 2; ++k) dst[n][k] = *(const PG8_LAS bf16x8*)(lds + PG8_SB(b, h) + boff + n * 2048 + k * 1024); } while (0)
; #define PG8_MMA(ai, bj, At, Bt) do { __builtin_amdgcn_s_setprio(1); _Pragma("unroll") for (int m = 0; m < 4; ++m) _Pragma("unroll") for (int n = 0; n < 2; ++n) _Pragma("unroll") for (int k = 0; k < 2; ++k) \
;         acc[ai][bj][m][n] = __builtin_amdgcn_mfma_f32_16x16x32_bf16(Bt[n][k], At[m][k], acc[ai][bj][m][n], 0, 0, 0); __builtin_amdgcn_s_setprio(0); } while (0)
; #define PG8_WAIT_V(n) asm volatile("s_waitcnt vmcnt(" #n ")" ::: "memory")
; #define PG8_WAIT_L(n) asm volatile("s_waitcnt lgkmcnt(" #n ")" ::: "memory")
; #define PG8_BAR __builtin_amdgcn_s_barrier()
; #define PG8_SCHED __builtin_amdgcn_sched_barrier(0)
; template <class Epi, class Sched, bool ALIGN_EPI = false, bool SP2 = false>
; __device__ __forceinline__ void gemm_phase(PG8_LAS unsigned char* lds, const Gemm g, const Sched& S, const Epi& E) {
;     ...
;             PG8_WAIT_V(8); PG8_WAIT_L(0); PG8_BAR; PG8_MMA(1, 0, At, B0); PG8_MMA(1, 1, At, B1); PG8_BAR; PG8_SCHED;
;             PG8_LDB(B0, 1, 0); PG8_LDB(B1, 1, 1); PG8_SCHED; PG8_LDA(At, 1, 0); PG8_STAGE(PG8_SA(0, 1), a2 + hstep, voffA);
;             PG8_WAIT_V(8); PG8_WAIT_L(0); PG8_BAR; PG8_MMA(0, 0, At, B0); PG8_MMA(0, 1, At, B1); PG8_BAR; PG8_SCHED;
	v_mfma_f32_16x16x32_bf16 v[64:67], v[184:187], v[216:219], 0
	v_mfma_f32_16x16x32_bf16 v[56:59], v[192:195], v[216:219], 0
	v_mfma_f32_16x16x32_bf16 v[48:51], v[184:187], v[224:227], 0
	v_mfma_f32_16x16x32_bf16 v[40:43], v[192:195], v[224:227], 0
	v_mfma_f32_16x16x32_bf16 v[32:35], v[184:187], v[232:235], 0
	v_mfma_f32_16x16x32_bf16 v[24:27], v[192:195], v[232:235], 0
	v_mfma_f32_16x16x32_bf16 v[16:19], v[184:187], v[240:243], 0
	v_mfma_f32_16x16x32_bf16 v[8:11], v[192:195], v[240:243], 0
	v_mfma_f32_16x16x32_bf16 v[64:67], v[188:191], v[220:223], v[64:67]
	v_mfma_f32_16x16x32_bf16 v[56:59], v[196:199], v[220:223], v[56:59]
	v_mfma_f32_16x16x32_bf16 v[48:51], v[188:191], v[228:231], v[48:51]
	v_mfma_f32_16x16x32_bf16 v[40:43], v[196:199], v[228:231], v[40:43]
	v_mfma_f32_16x16x32_bf16 v[32:35], v[188:191], v[236:239], v[32:35]
	v_mfma_f32_16x16x32_bf16 v[24:27], v[196:199], v[236:239], v[24:27]
	v_mfma_f32_16x16x32_bf16 v[16:19], v[188:191], v[244:247], v[16:19]
	v_mfma_f32_16x16x32_bf16 v[8:11], v[196:199], v[244:247], v[8:11]
	v_mfma_f32_16x16x32_bf16 v[60:63], v[200:203], v[216:219], 0
	v_mfma_f32_16x16x32_bf16 v[52:55], v[208:211], v[216:219], 0
	v_mfma_f32_16x16x32_bf16 v[44:47], v[200:203], v[224:227], 0
	v_mfma_f32_16x16x32_bf16 v[36:39], v[208:211], v[224:227], 0
	v_mfma_f32_16x16x32_bf16 v[28:31], v[200:203], v[232:235], 0
	v_mfma_f32_16x16x32_bf16 v[20:23], v[208:211], v[232:235], 0
	v_mfma_f32_16x16x32_bf16 v[12:15], v[200:203], v[240:243], 0
	v_mfma_f32_16x16x32_bf16 v[4:7], v[208:211], v[240:243], 0
	v_mfma_f32_16x16x32_bf16 v[60:63], v[204:207], v[220:223], v[60:63]
	v_mfma_f32_16x16x32_bf16 v[52:55], v[212:215], v[220:223], v[52:55]
	v_mfma_f32_16x16x32_bf16 v[44:47], v[204:207], v[228:231], v[44:47]
	v_mfma_f32_16x16x32_bf16 v[36:39], v[212:215], v[228:231], v[36:39]
	v_mfma_f32_16x16x32_bf16 v[28:31], v[204:207], v[236:239], v[28:31]
	v_mfma_f32_16x16x32_bf16 v[20:23], v[212:215], v[236:239], v[20:23]
	v_mfma_f32_16x16x32_bf16 v[12:15], v[204:207], v[244:247], v[12:15]
	v_mfma_f32_16x16x32_bf16 v[4:7], v[212:215], v[244:247], v[4:7]
	s_barrier
	s_setprio 0
	s_add_i32 s63, 0, 0x18000
	v_add_u32_e32 v161, s63, v153
	s_add_i32 s64, 0, 0x1c000
	ds_read_b128 v[184:187], v161
	ds_read_b128 v[188:191], v161 offset:1024
	ds_read_b128 v[192:195], v161 offset:2048
	ds_read_b128 v[196:199], v161 offset:3072
	v_add_u32_e32 v161, s64, v153
	ds_read_b128 v[200:203], v161
	ds_read_b128 v[204:207], v161 offset:1024
	ds_read_b128 v[208:211], v161 offset:2048
	ds_read_b128 v[212:215], v161 offset:3072
	s_add_u32 s22, s22, 0x80000
	s_addc_u32 s23, s23, 0
	s_mov_b32 m0, s31
	ds_read_b128 v[216:219], v155 offset:32768
	ds_read_b128 v[220:223], v155 offset:33792
	ds_read_b128 v[224:227], v155 offset:34816
	ds_read_b128 v[228:231], v155 offset:35840
	ds_read_b128 v[232:235], v155 offset:36864
	ds_read_b128 v[236:239], v155 offset:37888
	ds_read_b128 v[240:243], v155 offset:38912
	ds_read_b128 v[244:247], v155 offset:39936
	global_load_lds_dwordx4 v134, s[22:23]
	s_mov_b32 m0, s34
	s_nop 0
	global_load_lds_dwordx4 v132, s[22:23]
	s_waitcnt vmcnt(8)
	s_waitcnt lgkmcnt(0)
	s_setprio 1
	s_barrier
	v_mfma_f32_16x16x32_bf16 v[128:131], v[184:187], v[216:219], v[128:131]
	v_mfma_f32_16x16x32_bf16 v[120:123], v[192:195], v[216:219], v[120:123]
	v_mfma_f32_16x16x32_bf16 v[112:115], v[184:187], v[224:227], v[112:115]
	v_mfma_f32_16x16x32_bf16 v[104:107], v[192:195], v[224:227], v[104:107]
	v_mfma_f32_16x16x32_bf16 v[96:99], v[184:187], v[232:235], v[96:99]
	v_mfma_f32_16x16x32_bf16 v[88:91], v[192:195], v[232:235], v[88:91]
	v_mfma_f32_16x16x32_bf16 v[80:83], v[184:187], v[240:243], v[80:83]
	v_mfma_f32_16x16x32_bf16 v[72:75], v[192:195], v[240:243], v[72:75]
	v_mfma_f32_16x16x32_bf16 v[128:131], v[188:191], v[220:223], v[128:131]
	v_mfma_f32_16x16x32_bf16 v[120:123], v[196:199], v[220:223], v[120:123]
	v_mfma_f32_16x16x32_bf16 v[112:115], v[188:191], v[228:231], v[112:115]
	v_mfma_f32_16x16x32_bf16 v[104:107], v[196:199], v[228:231], v[104:107]
	v_mfma_f32_16x16x32_bf16 v[96:99], v[188:191], v[236:239], v[96:99]
	v_mfma_f32_16x16x32_bf16 v[88:91], v[196:199], v[236:239], v[88:91]
	v_mfma_f32_16x16x32_bf16 v[80:83], v[188:191], v[244:247], v[80:83]
	v_mfma_f32_16x16x32_bf16 v[72:75], v[196:199], v[244:247], v[72:75]
	v_mfma_f32_16x16x32_bf16 v[124:127], v[200:203], v[216:219], v[124:127]
	v_mfma_f32_16x16x32_bf16 v[116:119], v[208:211], v[216:219], v[116:119]
	v_mfma_f32_16x16x32_bf16 v[108:111], v[200:203], v[224:227], v[108:111]
	v_mfma_f32_16x16x32_bf16 v[100:103], v[208:211], v[224:227], v[100:103]
	v_mfma_f32_16x16x32_bf16 v[92:95], v[200:203], v[232:235], v[92:95]
	v_mfma_f32_16x16x32_bf16 v[84:87], v[208:211], v[232:235], v[84:87]
	v_mfma_f32_16x16x32_bf16 v[76:79], v[200:203], v[240:243], v[76:79]
	v_mfma_f32_16x16x32_bf16 v[68:71], v[208:211], v[240:243], v[68:71]
	v_mfma_f32_16x16x32_bf16 v[124:127], v[204:207], v[220:223], v[124:127]
	v_mfma_f32_16x16x32_bf16 v[116:119], v[212:215], v[220:223], v[116:119]
	v_mfma_f32_16x16x32_bf16 v[108:111], v[204:207], v[228:231], v[108:111]
	v_mfma_f32_16x16x32_bf16 v[100:103], v[212:215], v[228:231], v[100:103]
	v_mfma_f32_16x16x32_bf16 v[92:95], v[204:207], v[236:239], v[92:95]
	v_mfma_f32_16x16x32_bf16 v[84:87], v[212:215], v[236:239], v[84:87]
	v_mfma_f32_16x16x32_bf16 v[76:79], v[204:207], v[244:247], v[76:79]
	v_mfma_f32_16x16x32_bf16 v[68:71], v[212:215], v[244:247], v[68:71]
	s_barrier
; #define PG8_STAGE(bufoff, gbase, voff) do { _Pragma("unroll") for (int _i = 0; _i < 2; ++_i) \
;         __builtin_amdgcn_global_load_lds((const unsigned*)((const char*)(gbase) + (voff)[_i]), (PG8_LAS unsigned*)(lds + (bufoff) + ldsw + _i * 8192), 16, 0, 0); } while (0)
; #define PG8_LDA(dst, b, h) do { _Pragma("unroll") for (int m = 0; m < 4; ++m) _Pragma("unroll") for (int k = 0; k < 2; ++k) dst[m][k] = *(const PG8_LAS bf16x8*)(lds + PG8_SA(b, h) + aoff + m * 2048 + k * 1024); } while (0)
; #define PG8_MMA(ai, bj, At, Bt) do { __builtin_amdgcn_s_setprio(1); _Pragma("unroll") for (int m = 0; m < 4; ++m) _Pragma("unroll") for (int n = 0; n < 2; ++n) _Pragma("unroll") for (int k = 0; k < 2; ++k) \
;         acc[ai][bj][m][n] = __builtin_amdgcn_mfma_f32_16x16x32_bf16(Bt[n][k], At[m][k], acc[ai][bj][m][n], 0, 0, 0); __builtin_amdgcn_s_setprio(0); } while (0)
; #define PG8_WAIT_V(n) asm volatile("s_waitcnt vmcnt(" #n ")" ::: "memory")
; #define PG8_WAIT_L(n) asm volatile("s_waitcnt lgkmcnt(" #n ")" ::: "memory")
; #define PG8_BAR __builtin_amdgcn_s_barrier()
; #define PG8_SCHED __builtin_amdgcn_sched_barrier(0)
; template <class Epi, class Sched, bool ALIGN_EPI = false, bool SP2 = false>
; __device__ __forceinline__ void gemm_phase(PG8_LAS unsigned char* lds, const Gemm g, const Sched& S, const Epi& E) {
;     ...
;             PG8_LDA(At, 1, 1); PG8_STAGE(PG8_SB(1, 0), b3, voffB); PG8_STAGE(PG8_SB(1, 1), b3 + hstep, voffB); PG8_STAGE(PG8_SA(1, 0), a3, voffA);
;             PG8_WAIT_V(8); PG8_WAIT_L(0); PG8_BAR; PG8_MMA(1, 0, At, B0); PG8_MMA(1, 1, At, B1); PG8_BAR; PG8_SCHED;
	s_setprio 0
	s_add_i32 s22, s63, s27
	s_mov_b32 m0, s22
	ds_read_b128 v[216:219], v155 offset:49152
	ds_read_b128 v[220:223], v155 offset:50176
	ds_read_b128 v[224:227], v155 offset:51200
	ds_read_b128 v[228:231], v155 offset:52224
	ds_read_b128 v[232:235], v155 offset:53248
	ds_read_b128 v[236:239], v155 offset:54272
	ds_read_b128 v[240:243], v155 offset:55296
	ds_read_b128 v[244:247], v155 offset:56320
	s_add_u32 vcc_lo, s20, 0x80
	s_addc_u32 vcc_hi, s21, 0
	global_load_lds_dwordx4 v2, vcc
	s_add_i32 m0, s22, 0x2000
	s_add_u32 s20, s20, 0x80080
	s_addc_u32 s21, s21, 0
	s_add_i32 s22, s64, s27
	s_add_u32 vcc_lo, s20, 0xfff80000
	s_addc_u32 vcc_hi, s21, -1
	global_load_lds_dwordx4 v0, vcc
	s_mov_b32 m0, s22
	s_nop 0
	global_load_lds_dwordx4 v2, s[20:21]
	s_add_i32 m0, s22, 0x2000
	s_nop 0
	global_load_lds_dwordx4 v0, s[20:21]
	v_lshl_add_u64 v[150:151], v[248:249], 0, s[36:37]
	s_mov_b32 m0, s35
	s_nop 0
	global_load_lds_dwordx4 v[150:151], off
	v_lshl_add_u64 v[150:151], v[250:251], 0, s[36:37]
	s_mov_b32 m0, s42
	s_nop 0
	global_load_lds_dwordx4 v[150:151], off
	s_waitcnt vmcnt(8)
	s_waitcnt lgkmcnt(0)
	s_setprio 1
	s_barrier
	v_mfma_f32_16x16x32_bf16 v[64:67], v[184:187], v[216:219], v[64:67]
	v_mfma_f32_16x16x32_bf16 v[56:59], v[192:195], v[216:219], v[56:59]
	v_mfma_f32_16x16x32_bf16 v[48:51], v[184:187], v[224:227], v[48:51]
	v_mfma_f32_16x16x32_bf16 v[40:43], v[192:195], v[224:227], v[40:43]
	v_mfma_f32_16x16x32_bf16 v[32:35], v[184:187], v[232:235], v[32:35]
	v_mfma_f32_16x16x32_bf16 v[24:27], v[192:195], v[232:235], v[24:27]
	v_mfma_f32_16x16x32_bf16 v[16:19], v[184:187], v[240:243], v[16:19]
	v_mfma_f32_16x16x32_bf16 v[8:11], v[192:195], v[240:243], v[8:11]
	v_mfma_f32_16x16x32_bf16 v[64:67], v[188:191], v[220:223], v[64:67]
	v_mfma_f32_16x16x32_bf16 v[56:59], v[196:199], v[220:223], v[56:59]
	v_mfma_f32_16x16x32_bf16 v[48:51], v[188:191], v[228:231], v[48:51]
	v_mfma_f32_16x16x32_bf16 v[40:43], v[196:199], v[228:231], v[40:43]
	v_mfma_f32_16x16x32_bf16 v[32:35], v[188:191], v[236:239], v[32:35]
	v_mfma_f32_16x16x32_bf16 v[24:27], v[196:199], v[236:239], v[24:27]
	v_mfma_f32_16x16x32_bf16 v[16:19], v[188:191], v[244:247], v[16:19]
	v_mfma_f32_16x16x32_bf16 v[8:11], v[196:199], v[244:247], v[8:11]
	v_mfma_f32_16x16x32_bf16 v[60:63], v[200:203], v[216:219], v[60:63]
	v_mfma_f32_16x16x32_bf16 v[52:55], v[208:211], v[216:219], v[52:55]
	v_mfma_f32_16x16x32_bf16 v[44:47], v[200:203], v[224:227], v[44:47]
	v_mfma_f32_16x16x32_bf16 v[36:39], v[208:211], v[224:227], v[36:39]
	v_mfma_f32_16x16x32_bf16 v[28:31], v[200:203], v[232:235], v[28:31]
	v_mfma_f32_16x16x32_bf16 v[20:23], v[208:211], v[232:235], v[20:23]
	v_mfma_f32_16x16x32_bf16 v[12:15], v[200:203], v[240:243], v[12:15]
	v_mfma_f32_16x16x32_bf16 v[4:7], v[208:211], v[240:243], v[4:7]
	v_mfma_f32_16x16x32_bf16 v[60:63], v[204:207], v[220:223], v[60:63]
	v_mfma_f32_16x16x32_bf16 v[52:55], v[212:215], v[220:223], v[52:55]
	v_mfma_f32_16x16x32_bf16 v[44:47], v[204:207], v[228:231], v[44:47]
	v_mfma_f32_16x16x32_bf16 v[36:39], v[212:215], v[228:231], v[36:39]
	v_mfma_f32_16x16x32_bf16 v[28:31], v[204:207], v[236:239], v[28:31]
	v_mfma_f32_16x16x32_bf16 v[20:23], v[212:215], v[236:239], v[20:23]
	v_mfma_f32_16x16x32_bf16 v[12:15], v[204:207], v[244:247], v[12:15]
	v_mfma_f32_16x16x32_bf16 v[4:7], v[212:215], v[244:247], v[4:7]
	s_barrier
	s_setprio 0
	s_add_i32 s57, s57, 2
	s_add_u32 s18, s18, 0x100
	s_addc_u32 s19, s19, 0
	s_add_u32 s51, s51, 0x100
	s_addc_u32 s56, s56, 0
	s_cmp_gt_u32 s57, 29
